# Q-load deserialize + P1 two rows in flight + P0 transposes moved off gemv WGs
# baseline (speedup 1.0000x reference)
; #define LAS __attribute__((address_space(3)))
; __global__ void __launch_bounds__(512, 2) fwd_kernel(Args args) {
;     ...
;         if (blockIdx.x < 96) mod_gemv(X, args.in[2], args.in[3], args.in[4], args.in[5], mod, blockIdx.x * 64);
;     ...
;         LAS float* scr = (LAS float*)(X.lds + X.wave * 16384);
;         constexpr int I_IN = 16 * 70, I_UQ = 6 * 24, I_UKV = 4 * 32, I_O = 16 * 32, I_UP = 16 * 176, I_DN = 44 * 32;
;         constexpr int NITEMS = I_IN + I_UQ + I_UKV + I_O + I_UP + I_DN;
;         for (int it = X.gw; it < NITEMS; it += X.NGW) {
;             int r = it;
;             if (r < I_IN) { p0_transpose_item(args.in[7], 1024, 2240, Win_t, scr, r, X.lane); continue; } r -= I_IN;
;             if (r < I_UQ) { p0_transpose_item(args.in[10], 384, 768, Wuq_t, scr, r, X.lane); continue; } r -= I_UQ;
;             if (r < I_UKV) { p0_transpose_item(args.in[12], 256, 1024, Wukv_t, scr, r, X.lane); continue; } r -= I_UKV;
;             if (r < I_O) { p0_transpose_item(args.in[15], 1024, 1024, Wo_t, scr, r, X.lane); continue; } r -= I_O;
;             if (r < I_UP) { p0_transpose_item<true>(args.in[17], 1024, 5632, Wup_t, scr, r, X.lane); continue; } r -= I_UP;
;             p0_transpose_item(args.in[19], 2816, 1024, Wdn_t, scr, r, X.lane);
;         }
.LBB0_17:
	s_load_dwordx16 s[36:51], s[0:1], 0x40
	s_add_u32 s4, s56, 0x400000
	s_addc_u32 s5, s57, 0
	s_add_u32 s70, s56, 0x900000
	s_addc_u32 s71, s57, 0
	s_waitcnt lgkmcnt(0)
	v_writelane_b32 v244, s36, 11
	s_add_u32 s68, s56, 0xa00000
	s_addc_u32 s69, s57, 0
	v_writelane_b32 v244, s37, 12
	v_writelane_b32 v244, s38, 13
	v_writelane_b32 v244, s39, 14
	v_writelane_b32 v244, s40, 15
	v_writelane_b32 v244, s41, 16
	v_writelane_b32 v244, s42, 17
	v_writelane_b32 v244, s43, 18
	v_writelane_b32 v244, s44, 19
	v_writelane_b32 v244, s45, 20
	v_writelane_b32 v244, s46, 21
	s_add_u32 s8, s56, 0xb00000
	v_writelane_b32 v244, s47, 22
	s_addc_u32 s9, s57, 0
	v_writelane_b32 v244, s48, 23
	s_add_u32 s22, s56, 0xd00000
	v_writelane_b32 v244, s49, 24
	s_addc_u32 s23, s57, 0
	v_writelane_b32 v244, s50, 25
	s_add_u32 s0, s56, 0x1800000
	v_writelane_b32 v244, s51, 26
	s_addc_u32 s1, s57, 0
	v_writelane_b32 v244, s0, 27
	s_lshl_b32 s87, s58, 3
	v_lshlrev_b32_e32 v178, 3, v148
	v_writelane_b32 v244, s1, 28
	s_lshl_b32 s0, s84, 3
	s_add_i32 s86, s0, s60
	s_cmpk_gt_i32 s86, 0x17ef
	s_cbranch_scc1 .LBB0_52
	v_lshlrev_b32_e32 v1, 2, v6
	v_readlane_b32 s36, v244, 0
	v_and_b32_e32 v4, 0x7c, v1
	v_mov_b32_e32 v5, 0
	v_readlane_b32 s37, v244, 1
	v_readlane_b32 s38, v244, 2
	v_readlane_b32 s39, v244, 3
	v_readlane_b32 s40, v244, 4
	v_readlane_b32 s41, v244, 5
	v_readlane_b32 s42, v244, 6
	v_readlane_b32 s43, v244, 7
	s_lshl_b32 s0, s60, 14
	v_lshrrev_b32_e32 v3, 3, v148
	v_lshl_add_u64 v[8:9], s[42:43], 0, v[4:5]
	v_and_b32_e32 v1, 56, v178
	v_readlane_b32 s10, v244, 27
	v_lshl_add_u64 v[14:15], s[38:39], 0, v[4:5]
	v_readlane_b32 s36, v244, 11
	s_add_i32 s0, s0, 0
	v_lshrrev_b32_e32 v2, 5, v148
	v_mul_u32_u24_e32 v7, 0x84, v1
	v_lshlrev_b32_e32 v32, 1, v1
	v_mov_b32_e32 v33, v5
	v_readlane_b32 s11, v244, 28
	v_lshlrev_b32_e32 v1, 2, v3
	v_readlane_b32 s40, v244, 15
	v_readlane_b32 s41, v244, 16
	v_readlane_b32 s44, v244, 19
	v_readlane_b32 s45, v244, 20
	v_readlane_b32 s50, v244, 25
	v_readlane_b32 s51, v244, 26
	s_mov_b32 s1, 0
	v_add_u32_e32 v10, s0, v4
	s_movk_i32 s3, 0x84
	v_lshl_add_u64 v[12:13], s[10:11], 0, v[32:33]
	v_add3_u32 v7, s0, v7, v1
	v_or_b32_e32 v11, 8, v3
	v_or_b32_e32 v36, 16, v3
	v_or_b32_e32 v37, 24, v3
	v_lshl_add_u64 v[16:17], s[22:23], 0, v[32:33]
	v_lshl_add_u64 v[18:19], s[50:51], 0, v[4:5]
	v_lshl_add_u64 v[20:21], s[8:9], 0, v[32:33]
	v_lshl_add_u64 v[22:23], s[44:45], 0, v[4:5]
	v_lshl_add_u64 v[24:25], s[68:69], 0, v[32:33]
	v_lshl_add_u64 v[26:27], s[40:41], 0, v[4:5]
	v_lshl_add_u64 v[28:29], s[70:71], 0, v[32:33]
	v_lshl_add_u64 v[30:31], s[30:31], 0, v[4:5]
	v_lshl_add_u64 v[32:33], s[4:5], 0, v[32:33]
	v_mov_b32_e32 v1, v2
	s_movk_i32 s24, 0x5800
	s_movk_i32 s25, 0xc00
	s_movk_i32 s26, 0x2300
	s_cmpk_lt_u32 s2, 0x60
	s_cbranch_scc1 .LBB0_52
	s_sub_i32 s27, s2, 0x60
	s_lshl_b32 s27, s27, 3
	s_add_i32 s27, s27, s60
	v_readlane_b32 s37, v244, 12
	v_readlane_b32 s38, v244, 13
	v_readlane_b32 s39, v244, 14
	v_readlane_b32 s42, v244, 17
	v_readlane_b32 s43, v244, 18
	v_readlane_b32 s46, v244, 21
	v_readlane_b32 s47, v244, 22
	v_readlane_b32 s48, v244, 23
	v_readlane_b32 s49, v244, 24
	s_branch .LBB0_20
.LBB0_19:
	s_add_i32 s27, s27, s87
	s_addk_i32 s27, 0xfd00
	s_cmpk_gt_i32 s27, 0x17ef
	s_cbranch_scc1 .LBB0_52

; __device__ __forceinline__ unsigned cvtpk(float lo, float hi) { unsigned r; asm volatile("v_cvt_pk_bf16_f32 %0, %1, %2" : "=v"(r) : "v"(lo), "v"(hi)); return r; }
; __device__ __forceinline__ void modnorm_phase(const Ctx& X, const float* src_p, const float* src_s, const float* g, const float* mod, int sh_off, int sc_off, bf16_t* H) {
;     ...
;         for (int r = 0; r < 16; ++r) {
;             const float* xr = src + (size_t)(t0 + r) * DM + X.lane * 4;
;             f32x4 v[4]; float ss = 0.f;
; #pragma unroll
;             for (int j = 0; j < 4; ++j) { v[j] = *(const f32x4*)(xr + 256 * j); ss += (v[j].x * v[j].x + v[j].y * v[j].y) + (v[j].z * v[j].z + v[j].w * v[j].w); }
;             const float rstd = rsqrtf(wave_sum(ss) * (1.f / DM) + EPS);
;             bf16_t* orow = H + (size_t)(t0 + r) * DM + X.lane * 4;
; #pragma unroll
;             for (int j = 0; j < 4; ++j) { const f32x4 o = v[j] * rstd * gs[j] + sh[j]; u32x2 w; w.x = cvtpk(o.x, o.y); w.y = cvtpk(o.z, o.w); *(u32x2*)(orow + 256 * j) = w; }
.LBB0_71:
	s_add_i32 s6, s3, s13
	s_ashr_i32 s7, s6, 31
	s_lshl_b64 s[14:15], s[6:7], 12
	v_lshl_add_u64 v[58:59], v[22:23], 0, s[14:15]
	global_load_dwordx4 v[46:49], v[58:59], off
	global_load_dwordx4 v[50:53], v[58:59], off offset:1024
	global_load_dwordx4 v[54:57], v[58:59], off offset:3072
	s_nop 0
	global_load_dwordx4 v[58:61], v[58:59], off offset:2048
	v_mov_b32_e32 v77, 0
	v_mov_b32_e32 v45, 0
	s_add_i32 s0, s6, 1
	s_lshl_b64 s[6:7], s[6:7], 11
	s_ashr_i32 s1, s0, 31
	v_lshl_add_u64 v[62:63], v[18:19], 0, s[6:7]
	s_lshl_b64 s[6:7], s[0:1], 12
	v_lshl_add_u64 v[64:65], v[22:23], 0, s[6:7]
	s_lshl_b64 s[0:1], s[0:1], 11
	global_load_dwordx4 v[84:87], v[64:65], off
	global_load_dwordx4 v[88:91], v[64:65], off offset:1024
	global_load_dwordx4 v[92:95], v[64:65], off offset:2048
	global_load_dwordx4 v[96:99], v[64:65], off offset:3072
	s_add_i32 s13, s13, 2
	s_cmp_eq_u32 s13, 16
	s_waitcnt vmcnt(7)
	v_pk_mul_f32 v[66:67], v[48:49], v[48:49]
	v_pk_mul_f32 v[68:69], v[46:47], v[46:47]
	s_waitcnt vmcnt(6)
	v_pk_mul_f32 v[70:71], v[52:53], v[52:53]
	v_pk_mul_f32 v[72:73], v[50:51], v[50:51]
	v_pk_mov_b32 v[78:79], v[68:69], v[66:67] op_sel:[1,0]
	v_mov_b32_e32 v69, v67
	v_pk_mov_b32 v[66:67], v[72:73], v[70:71] op_sel:[1,0]
	v_mov_b32_e32 v73, v71
	s_waitcnt vmcnt(4)
	v_mul_f32_e32 v74, v59, v59
	v_mul_f32_e32 v76, v61, v61
	v_pk_add_f32 v[68:69], v[78:79], v[68:69]
	v_pk_add_f32 v[66:67], v[66:67], v[72:73]
	v_mul_f32_e32 v80, v54, v54
	v_mul_f32_e32 v81, v55, v55
	v_mul_f32_e32 v82, v56, v56
	v_mul_f32_e32 v83, v57, v57
	v_pk_fma_f32 v[70:71], v[58:59], v[58:59], v[74:75] op_sel_hi:[1,1,0]
	v_pk_fma_f32 v[74:75], v[60:61], v[60:61], v[76:77] op_sel_hi:[1,1,0]
	v_pk_add_f32 v[68:69], v[68:69], v[68:69] op_sel:[0,1] op_sel_hi:[1,0]
	v_pk_add_f32 v[66:67], v[66:67], v[66:67] op_sel:[0,1] op_sel_hi:[1,0]
	v_mov_b32_e32 v71, v82
	v_mov_b32_e32 v75, v83
	v_mov_b32_e32 v69, v80
	v_mov_b32_e32 v67, v81
	v_pk_add_f32 v[70:71], v[70:71], v[74:75]
	v_pk_add_f32 v[66:67], v[68:69], v[66:67]
	v_mov_b32_e32 v75, 0
	v_pk_add_f32 v[66:67], v[66:67], v[70:71]
	s_nop 0
	v_add_f32_e32 v66, v66, v67
	s_nop 1
	v_add_f32_dpp v66, v66, v66 quad_perm:[1,0,3,2] row_mask:0xf bank_mask:0xf bound_ctrl:1
	s_nop 1
	v_add_f32_dpp v66, v66, v66 quad_perm:[2,3,0,1] row_mask:0xf bank_mask:0xf bound_ctrl:1
	s_nop 1
	v_add_f32_dpp v66, v66, v66 row_half_mirror row_mask:0xf bank_mask:0xf bound_ctrl:1
	s_nop 1
	v_add_f32_dpp v66, v66, v66 row_mirror row_mask:0xf bank_mask:0xf bound_ctrl:1
	s_nop 1
	v_mov_b32_dpp v45, v66 row_bcast:15 row_mask:0xa bank_mask:0xf
	v_add_f32_e32 v45, v66, v45
	s_nop 1
	v_mov_b32_dpp v77, v45 row_bcast:31 row_mask:0xc bank_mask:0xf
	v_add_f32_e32 v45, v45, v77
	s_nop 0
	v_readlane_b32 s6, v45, 63
	s_nop 1
	v_fma_f32 v45, s6, v44, v43
	v_mul_f32_e32 v66, 0x4b800000, v45
	v_cmp_gt_f32_e32 vcc, s11, v45
	s_nop 1
	v_cndmask_b32_e32 v45, v45, v66, vcc
	v_rsq_f32_e32 v45, v45
	s_nop 0
	v_mul_f32_e32 v66, 0x45800000, v45
	v_cndmask_b32_e32 v66, v45, v66, vcc
	v_pk_mul_f32 v[46:47], v[46:47], v[66:67] op_sel_hi:[1,0]
	v_pk_mul_f32 v[48:49], v[48:49], v[66:67] op_sel_hi:[1,0]
	v_pk_fma_f32 v[46:47], v[26:27], v[46:47], v[0:1]
	v_pk_mul_f32 v[50:51], v[50:51], v[66:67] op_sel_hi:[1,0]
	v_pk_mul_f32 v[52:53], v[52:53], v[66:67] op_sel_hi:[1,0]
	v_pk_fma_f32 v[48:49], v[24:25], v[48:49], v[2:3]
	v_cvt_pk_bf16_f32 v46, v46, v47
	v_pk_mul_f32 v[58:59], v[58:59], v[66:67] op_sel_hi:[1,0]
	v_cvt_pk_bf16_f32 v47, v48, v49
	v_pk_mul_f32 v[60:61], v[60:61], v[66:67] op_sel_hi:[1,0]
	v_pk_fma_f32 v[52:53], v[28:29], v[52:53], v[6:7]
	v_pk_fma_f32 v[50:51], v[30:31], v[50:51], v[4:5]
	global_store_dwordx2 v[62:63], v[46:47], off
	v_cvt_pk_bf16_f32 v46, v50, v51
	v_cvt_pk_bf16_f32 v47, v52, v53
	v_pk_mul_f32 v[54:55], v[54:55], v[66:67] op_sel_hi:[1,0]
	v_pk_mul_f32 v[56:57], v[56:57], v[66:67] op_sel_hi:[1,0]
	v_pk_fma_f32 v[60:61], v[32:33], v[60:61], v[10:11]
	v_pk_fma_f32 v[58:59], v[34:35], v[58:59], v[8:9]
	global_store_dwordx2 v[62:63], v[46:47], off offset:512
	v_cvt_pk_bf16_f32 v46, v58, v59
	v_cvt_pk_bf16_f32 v47, v60, v61
	v_pk_fma_f32 v[56:57], v[36:37], v[56:57], v[14:15]
	v_pk_fma_f32 v[54:55], v[38:39], v[54:55], v[12:13]
	global_store_dwordx2 v[62:63], v[46:47], off offset:1024
	v_cvt_pk_bf16_f32 v46, v54, v55
	v_cvt_pk_bf16_f32 v47, v56, v57
	global_store_dwordx2 v[62:63], v[46:47], off offset:1536
	v_mov_b32_e32 v45, 0
	v_lshl_add_u64 v[62:63], v[18:19], 0, s[0:1]
	s_waitcnt vmcnt(7)
; __device__ __forceinline__ unsigned cvtpk(float lo, float hi) { unsigned r; asm volatile("v_cvt_pk_bf16_f32 %0, %1, %2" : "=v"(r) : "v"(lo), "v"(hi)); return r; }
; __device__ __forceinline__ void modnorm_phase(const Ctx& X, const float* src_p, const float* src_s, const float* g, const float* mod, int sh_off, int sc_off, bf16_t* H) {
;     ...
;         for (int r = 0; r < 16; ++r) {
;             const float* xr = src + (size_t)(t0 + r) * DM + X.lane * 4;
;             f32x4 v[4]; float ss = 0.f;
; #pragma unroll
;             for (int j = 0; j < 4; ++j) { v[j] = *(const f32x4*)(xr + 256 * j); ss += (v[j].x * v[j].x + v[j].y * v[j].y) + (v[j].z * v[j].z + v[j].w * v[j].w); }
;             const float rstd = rsqrtf(wave_sum(ss) * (1.f / DM) + EPS);
;             bf16_t* orow = H + (size_t)(t0 + r) * DM + X.lane * 4;
; #pragma unroll
;             for (int j = 0; j < 4; ++j) { const f32x4 o = v[j] * rstd * gs[j] + sh[j]; u32x2 w; w.x = cvtpk(o.x, o.y); w.y = cvtpk(o.z, o.w); *(u32x2*)(orow + 256 * j) = w; }
	v_pk_mul_f32 v[64:65], v[86:87], v[86:87]
	v_pk_mul_f32 v[66:67], v[84:85], v[84:85]
	s_waitcnt vmcnt(6)
	v_pk_mul_f32 v[68:69], v[90:91], v[90:91]
	v_pk_mul_f32 v[70:71], v[88:89], v[88:89]
	v_pk_mov_b32 v[76:77], v[66:67], v[64:65] op_sel:[1,0]
	v_mov_b32_e32 v67, v65
	v_pk_mov_b32 v[64:65], v[70:71], v[68:69] op_sel:[1,0]
	v_mov_b32_e32 v71, v69
	s_waitcnt vmcnt(5)
	v_mul_f32_e32 v72, v93, v93
	v_mul_f32_e32 v74, v95, v95
	v_pk_add_f32 v[66:67], v[76:77], v[66:67]
	v_pk_add_f32 v[64:65], v[64:65], v[70:71]
	s_waitcnt vmcnt(4)
	v_mul_f32_e32 v78, v96, v96
	v_mul_f32_e32 v79, v97, v97
	v_mul_f32_e32 v80, v98, v98
	v_mul_f32_e32 v81, v99, v99
	v_pk_fma_f32 v[68:69], v[92:93], v[92:93], v[72:73] op_sel_hi:[1,1,0]
	v_pk_fma_f32 v[72:73], v[94:95], v[94:95], v[74:75] op_sel_hi:[1,1,0]
	v_pk_add_f32 v[66:67], v[66:67], v[66:67] op_sel:[0,1] op_sel_hi:[1,0]
	v_pk_add_f32 v[64:65], v[64:65], v[64:65] op_sel:[0,1] op_sel_hi:[1,0]
	v_mov_b32_e32 v69, v80
	v_mov_b32_e32 v73, v81
	v_mov_b32_e32 v67, v78
	v_mov_b32_e32 v65, v79
	v_pk_add_f32 v[68:69], v[68:69], v[72:73]
	v_pk_add_f32 v[64:65], v[66:67], v[64:65]
	s_nop 0
	v_pk_add_f32 v[64:65], v[64:65], v[68:69]
	s_nop 0
	v_add_f32_e32 v64, v64, v65
	s_nop 1
	v_add_f32_dpp v64, v64, v64 quad_perm:[1,0,3,2] row_mask:0xf bank_mask:0xf bound_ctrl:1
	s_nop 1
	v_add_f32_dpp v64, v64, v64 quad_perm:[2,3,0,1] row_mask:0xf bank_mask:0xf bound_ctrl:1
	s_nop 1
	v_add_f32_dpp v64, v64, v64 row_half_mirror row_mask:0xf bank_mask:0xf bound_ctrl:1
	s_nop 1
	v_add_f32_dpp v64, v64, v64 row_mirror row_mask:0xf bank_mask:0xf bound_ctrl:1
	s_nop 1
	v_mov_b32_dpp v45, v64 row_bcast:15 row_mask:0xa bank_mask:0xf
	v_add_f32_e32 v45, v64, v45
	s_nop 1
	v_mov_b32_dpp v75, v45 row_bcast:31 row_mask:0xc bank_mask:0xf
	v_add_f32_e32 v45, v45, v75
	s_nop 0
	v_readlane_b32 s0, v45, 63
	s_nop 1
	v_fma_f32 v45, s0, v44, v43
	v_mul_f32_e32 v64, 0x4b800000, v45
	v_cmp_gt_f32_e32 vcc, s11, v45
	s_nop 1
	v_cndmask_b32_e32 v45, v45, v64, vcc
	v_rsq_f32_e32 v45, v45
	s_nop 0
	v_mul_f32_e32 v64, 0x45800000, v45
	v_cndmask_b32_e32 v64, v45, v64, vcc
	v_pk_mul_f32 v[84:85], v[84:85], v[64:65] op_sel_hi:[1,0]
	v_pk_mul_f32 v[86:87], v[86:87], v[64:65] op_sel_hi:[1,0]
	v_pk_fma_f32 v[84:85], v[26:27], v[84:85], v[0:1]
	v_pk_mul_f32 v[88:89], v[88:89], v[64:65] op_sel_hi:[1,0]
	v_pk_mul_f32 v[90:91], v[90:91], v[64:65] op_sel_hi:[1,0]
	v_pk_fma_f32 v[86:87], v[24:25], v[86:87], v[2:3]
	v_cvt_pk_bf16_f32 v84, v84, v85
	v_pk_mul_f32 v[92:93], v[92:93], v[64:65] op_sel_hi:[1,0]
	v_cvt_pk_bf16_f32 v85, v86, v87
	v_pk_mul_f32 v[94:95], v[94:95], v[64:65] op_sel_hi:[1,0]
	v_pk_fma_f32 v[90:91], v[28:29], v[90:91], v[6:7]
	v_pk_fma_f32 v[88:89], v[30:31], v[88:89], v[4:5]
	global_store_dwordx2 v[62:63], v[84:85], off
	v_cvt_pk_bf16_f32 v84, v88, v89
	v_cvt_pk_bf16_f32 v85, v90, v91
	v_pk_mul_f32 v[96:97], v[96:97], v[64:65] op_sel_hi:[1,0]
	v_pk_mul_f32 v[98:99], v[98:99], v[64:65] op_sel_hi:[1,0]
	v_pk_fma_f32 v[94:95], v[32:33], v[94:95], v[10:11]
	v_pk_fma_f32 v[92:93], v[34:35], v[92:93], v[8:9]
	global_store_dwordx2 v[62:63], v[84:85], off offset:512
	v_cvt_pk_bf16_f32 v84, v92, v93
	v_cvt_pk_bf16_f32 v85, v94, v95
	v_pk_fma_f32 v[98:99], v[36:37], v[98:99], v[14:15]
	v_pk_fma_f32 v[96:97], v[38:39], v[96:97], v[12:13]
	global_store_dwordx2 v[62:63], v[84:85], off offset:1024
	v_cvt_pk_bf16_f32 v84, v96, v97
	v_cvt_pk_bf16_f32 v85, v98, v99
	global_store_dwordx2 v[62:63], v[84:85], off offset:1536
	s_cbranch_scc0 .LBB0_71
	s_add_i32 s12, s12, s87
	s_add_i32 s3, s3, s10
	s_cmpk_gt_i32 s12, 0x17ff
	s_cbranch_scc0 .LBB0_70

; __global__ void __launch_bounds__(512, 2) fwd_kernel(Args args) {
;     ...
;         for (int L = X.vcu; L < 1536; L += X.G) {
;             int rowbase, h, q0, seq;
;             if (L < 1024) { const int bh = L >> 5, qb = L & 31; rowbase = T_P + (bh >> 2) * S_S; h = bh & 3; q0 = qb * 256; seq = S_S; }
;             else { const int l2 = L - 1024; const int bh = l2 >> 3, qb = l2 & 7; rowbase = (bh >> 2) * S_P; h = bh & 3; q0 = qb * 256; seq = S_P; }
;     ...
;             att::attn_unit(QB + (size_t)(rowbase + q0) * 768 + h * 192, KVB + (size_t)rowbase * 1024 + h * 256, KVB + (size_t)rowbase * 1024 + h * 256 + 128,
;                            KR + (size_t)rowbase * 64, YC + (size_t)(rowbase + q0) * 1024 + 512 + h * 128, cosT + q0 * 32, sinT + q0 * 32, seq, (char*)lds);
.LBB0_390:
	s_lshl_b32 s3, s97, 6
	s_cmpk_gt_i32 s97, 0x3ff
	s_mov_b64 s[66:67], -1
	s_cbranch_scc0 .LBB0_392
	s_add_i32 s0, s3, 0x7fff0000
	s_lshr_b32 s1, s97, 3
	s_and_b32 s0, s0, 0x7ffff800
	s_mov_b64 s[66:67], 0
.LBB0_392:
	s_andn2_b64 vcc, exec, s[66:67]
	s_cbranch_vccnz .LBB0_394
	s_and_b32 s0, s3, 0xffffe000
	s_lshr_b32 s1, s97, 5
	s_add_i32 s0, s0, 0x8000
	s_movk_i32 s33, 0x80
	s_movk_i32 s3, 0x1f00
	s_branch .LBB0_395

; __device__ __forceinline__ void attn_unit(const bf16_t* __restrict__ Qb, const bf16_t* __restrict__ Kh, const bf16_t* __restrict__ Vh, const bf16_t* __restrict__ Krh, ...
;     ...
;     const bf16_t* Qw = Qb + (long)(wid * 32 + r32) * 768 + hi * 8;
; #pragma unroll
;     for (int d0 = 0; d0 < 8; ++d0) { float qf_[8]; unpack8(*reinterpret_cast<const u32x4*>(Qw + d0 * 16), qf_);
; #pragma unroll
;         for (int j = 0; j < 8; ++j) qf_[j] *= QC;
;         qr[d0] = __builtin_bit_cast(bf16x8, pack8(qf_)); }
; __global__ void __launch_bounds__(512, 2) fwd_kernel(Args args) {
;     ...
;             if (L < 1024) { const int bh = L >> 5, qb = L & 31; rowbase = T_P + (bh >> 2) * S_S; h = bh & 3; q0 = qb * 256; seq = S_S; }
;             else { const int l2 = L - 1024; const int bh = l2 >> 3, qb = l2 & 7; rowbase = (bh >> 2) * S_P; h = bh & 3; q0 = qb * 256; seq = S_P; }
;     ...
;             att::attn_unit(QB + (size_t)(rowbase + q0) * 768 + h * 192, KVB + (size_t)rowbase * 1024 + h * 256, KVB + (size_t)rowbase * 1024 + h * 256 + 128,
;                            KR + (size_t)rowbase * 64, YC + (size_t)(rowbase + q0) * 1024 + 512 + h * 128, cosT + q0 * 32, sinT + q0 * 32, seq, (char*)lds);
.LBB0_395:
	s_lshl_b32 s6, s97, 8
	s_and_b32 s10, s6, s3
	s_add_i32 s66, s0, s10
	s_and_b32 s3, s1, 3
	s_ashr_i32 s67, s66, 31
	s_mul_i32 s6, s66, 0x600
	s_mul_hi_i32 s1, s66, 0x600
	s_add_u32 s6, s18, s6
	s_addc_u32 s1, s19, s1
	s_mul_i32 s7, s3, 0x180
	s_add_u32 s74, s6, s7
	s_addc_u32 s75, s1, 0
	s_ashr_i32 s1, s0, 31
	s_lshl_b64 s[6:7], s[0:1], 11
	s_add_u32 s6, s4, s6
	s_addc_u32 s7, s5, s7
	s_lshl_b32 s11, s3, 9
	s_add_u32 s68, s6, s11
	s_addc_u32 s69, s7, 0
	s_lshl_b64 s[0:1], s[0:1], 7
	s_add_u32 s0, s14, s0
	s_addc_u32 s1, s15, s1
	s_lshl_b32 s6, s10, 7
	v_mov_b32_e32 v9, v210
	s_add_u32 s72, s76, s6
	s_addc_u32 s73, s77, 0
	v_ashrrev_i32_e32 v10, 6, v9
	v_and_b32_e32 v177, 31, v9
	v_and_b32_e32 v0, 0x3fffffc0, v9
	v_lshlrev_b32_e32 v186, 5, v10
	s_add_u32 s70, s78, s6
	v_bfe_u32 v179, v9, 5, 1
	v_lshl_add_u32 v183, v0, 2, s80
	v_or_b32_e32 v11, v186, v177
	v_mov_b64_e32 v[0:1], s[74:75]
	s_movk_i32 s6, 0x600
	v_mad_i64_i32 v[0:1], s[6:7], v11, s6, v[0:1]
	v_lshlrev_b32_e32 v184, 4, v179
	v_lshl_add_u64 v[2:3], v[0:1], 0, v[184:185]
	global_load_dwordx4 v[64:67], v[2:3], off
	global_load_dwordx4 v[68:71], v[2:3], off offset:32
	global_load_dwordx4 v[72:75], v[2:3], off offset:64
	global_load_dwordx4 v[76:79], v[2:3], off offset:96
	global_load_dwordx4 v[80:83], v[2:3], off offset:128
	global_load_dwordx4 v[84:87], v[2:3], off offset:160
	global_load_dwordx4 v[88:91], v[2:3], off offset:192
	global_load_dwordx4 v[92:95], v[2:3], off offset:224
	s_addc_u32 s71, s79, 0
	v_and_b32_e32 v8, 63, v9
	s_cmp_lg_u32 0, -1
	s_cselect_b32 s10, 0, 0
	s_add_i32 s7, s10, 0x12000
	v_lshlrev_b32_e32 v211, 8, v177
	v_lshlrev_b32_e32 v215, 7, v177
	s_mov_b32 s28, 3
	s_mov_b32 vcc_lo, 2
	v_lshl_add_u32 v187, v177, 2, v183
	s_waitcnt vmcnt(7)
	v_lshlrev_b32_e32 v0, 16, v64
	v_and_b32_e32 v1, 0xffff0000, v64
	v_lshlrev_b32_e32 v4, 16, v65
	v_and_b32_e32 v5, 0xffff0000, v65
	v_lshlrev_b32_e32 v12, 16, v66
	v_and_b32_e32 v6, 0xffff0000, v66
	v_lshlrev_b32_e32 v13, 16, v67
	v_and_b32_e32 v7, 0xffff0000, v67
	v_mul_f32_e32 v4, 0x3dd53b94, v4
	v_mul_f32_e32 v5, 0x3dd53b94, v5
	v_mul_f32_e32 v6, 0x3dd53b94, v6
	v_mul_f32_e32 v7, 0x3dd53b94, v7
	v_mul_f32_e32 v0, 0x3dd53b94, v0
	v_mul_f32_e32 v1, 0x3dd53b94, v1
	v_mul_f32_e32 v12, 0x3dd53b94, v12
	v_mul_f32_e32 v13, 0x3dd53b94, v13
	v_cvt_pk_bf16_f32 v128, v0, v1
	v_cvt_pk_bf16_f32 v129, v4, v5
	v_cvt_pk_bf16_f32 v130, v12, v6
	v_cvt_pk_bf16_f32 v131, v13, v7
	s_waitcnt vmcnt(6)
	v_lshlrev_b32_e32 v0, 16, v68
	v_and_b32_e32 v1, 0xffff0000, v68
	v_lshlrev_b32_e32 v4, 16, v69
	v_and_b32_e32 v5, 0xffff0000, v69
	v_lshlrev_b32_e32 v12, 16, v70
	v_and_b32_e32 v6, 0xffff0000, v70
	v_lshlrev_b32_e32 v13, 16, v71
	v_and_b32_e32 v7, 0xffff0000, v71
	v_mul_f32_e32 v4, 0x3dd53b94, v4
	v_mul_f32_e32 v5, 0x3dd53b94, v5
	v_mul_f32_e32 v6, 0x3dd53b94, v6
	v_mul_f32_e32 v7, 0x3dd53b94, v7
	v_mul_f32_e32 v0, 0x3dd53b94, v0
	v_mul_f32_e32 v1, 0x3dd53b94, v1
	v_mul_f32_e32 v12, 0x3dd53b94, v12
	v_mul_f32_e32 v13, 0x3dd53b94, v13
	v_cvt_pk_bf16_f32 v132, v0, v1
	v_cvt_pk_bf16_f32 v133, v4, v5
	v_cvt_pk_bf16_f32 v134, v12, v6
	v_cvt_pk_bf16_f32 v135, v13, v7
	s_waitcnt vmcnt(5)
	v_lshlrev_b32_e32 v0, 16, v72
	v_and_b32_e32 v1, 0xffff0000, v72
	v_lshlrev_b32_e32 v4, 16, v73
	v_and_b32_e32 v5, 0xffff0000, v73
	v_lshlrev_b32_e32 v12, 16, v74
	v_and_b32_e32 v6, 0xffff0000, v74
	v_lshlrev_b32_e32 v13, 16, v75
	v_and_b32_e32 v7, 0xffff0000, v75
	v_mul_f32_e32 v4, 0x3dd53b94, v4
	v_mul_f32_e32 v5, 0x3dd53b94, v5
	v_mul_f32_e32 v6, 0x3dd53b94, v6
	v_mul_f32_e32 v7, 0x3dd53b94, v7
	v_mul_f32_e32 v0, 0x3dd53b94, v0
	v_mul_f32_e32 v1, 0x3dd53b94, v1
	v_mul_f32_e32 v12, 0x3dd53b94, v12
	v_mul_f32_e32 v13, 0x3dd53b94, v13
	v_cvt_pk_bf16_f32 v136, v0, v1
	v_cvt_pk_bf16_f32 v137, v4, v5
	v_cvt_pk_bf16_f32 v138, v12, v6
	v_cvt_pk_bf16_f32 v139, v13, v7
	s_waitcnt vmcnt(4)
	v_lshlrev_b32_e32 v0, 16, v76
	v_and_b32_e32 v1, 0xffff0000, v76
	v_lshlrev_b32_e32 v4, 16, v77
	v_and_b32_e32 v5, 0xffff0000, v77
	v_lshlrev_b32_e32 v12, 16, v78
	v_and_b32_e32 v6, 0xffff0000, v78
	v_lshlrev_b32_e32 v13, 16, v79
	v_and_b32_e32 v7, 0xffff0000, v79
	v_mul_f32_e32 v4, 0x3dd53b94, v4
	v_mul_f32_e32 v5, 0x3dd53b94, v5
	v_mul_f32_e32 v6, 0x3dd53b94, v6
	v_mul_f32_e32 v7, 0x3dd53b94, v7
	v_mul_f32_e32 v0, 0x3dd53b94, v0
	v_mul_f32_e32 v1, 0x3dd53b94, v1
	v_mul_f32_e32 v12, 0x3dd53b94, v12
	v_mul_f32_e32 v13, 0x3dd53b94, v13
	v_cvt_pk_bf16_f32 v140, v0, v1
	v_cvt_pk_bf16_f32 v141, v4, v5
	v_cvt_pk_bf16_f32 v142, v12, v6
	v_cvt_pk_bf16_f32 v143, v13, v7
	s_waitcnt vmcnt(3)
	v_lshlrev_b32_e32 v0, 16, v80
	v_and_b32_e32 v1, 0xffff0000, v80
	v_lshlrev_b32_e32 v4, 16, v81
	v_and_b32_e32 v5, 0xffff0000, v81
	v_lshlrev_b32_e32 v12, 16, v82
	v_and_b32_e32 v6, 0xffff0000, v82
	v_lshlrev_b32_e32 v13, 16, v83
	v_and_b32_e32 v7, 0xffff0000, v83
	v_mul_f32_e32 v4, 0x3dd53b94, v4
	v_mul_f32_e32 v5, 0x3dd53b94, v5
	v_mul_f32_e32 v6, 0x3dd53b94, v6
	v_mul_f32_e32 v7, 0x3dd53b94, v7
	v_mul_f32_e32 v0, 0x3dd53b94, v0
	v_mul_f32_e32 v1, 0x3dd53b94, v1
	v_mul_f32_e32 v12, 0x3dd53b94, v12
	v_mul_f32_e32 v13, 0x3dd53b94, v13
	v_cvt_pk_bf16_f32 v144, v0, v1
	v_cvt_pk_bf16_f32 v145, v4, v5
	v_cvt_pk_bf16_f32 v146, v12, v6
	v_cvt_pk_bf16_f32 v147, v13, v7
	s_waitcnt vmcnt(2)
	v_lshlrev_b32_e32 v0, 16, v84
	v_and_b32_e32 v1, 0xffff0000, v84
	v_lshlrev_b32_e32 v4, 16, v85
	v_and_b32_e32 v5, 0xffff0000, v85
	v_lshlrev_b32_e32 v12, 16, v86
	v_and_b32_e32 v6, 0xffff0000, v86
	v_lshlrev_b32_e32 v13, 16, v87
	v_and_b32_e32 v7, 0xffff0000, v87
	v_mul_f32_e32 v4, 0x3dd53b94, v4
	v_mul_f32_e32 v5, 0x3dd53b94, v5
	v_mul_f32_e32 v6, 0x3dd53b94, v6
	v_mul_f32_e32 v7, 0x3dd53b94, v7
	v_mul_f32_e32 v0, 0x3dd53b94, v0
	v_mul_f32_e32 v1, 0x3dd53b94, v1
	v_mul_f32_e32 v12, 0x3dd53b94, v12
	v_mul_f32_e32 v13, 0x3dd53b94, v13
	v_cvt_pk_bf16_f32 v148, v0, v1
	v_cvt_pk_bf16_f32 v149, v4, v5
	v_cvt_pk_bf16_f32 v150, v12, v6
	v_cvt_pk_bf16_f32 v151, v13, v7
	s_waitcnt vmcnt(1)
; __device__ __forceinline__ void attn_unit(const bf16_t* __restrict__ Qb, const bf16_t* __restrict__ Kh, const bf16_t* __restrict__ Vh, const bf16_t* __restrict__ Krh, ...
;     ...
;     for (int d0 = 0; d0 < 8; ++d0) { float qf_[8]; unpack8(*reinterpret_cast<const u32x4*>(Qw + d0 * 16), qf_);
; #pragma unroll
;         for (int j = 0; j < 8; ++j) qf_[j] *= QC;
;         qr[d0] = __builtin_bit_cast(bf16x8, pack8(qf_)); }
;     {
;         const float* cp = cosq + (wid * 32 + r32) * 32 + hi * 8; const float* sp = sinq + (wid * 32 + r32) * 32 + hi * 8;
; #pragma unroll
;         for (int g = 0; g < 2; ++g) {
;             float c[8], s[8], x1[8], x2[8], y1[8], y2[8];
;             *(f32x4*)&c[0] = *(const f32x4*)(cp + g * 16); *(f32x4*)&c[4] = *(const f32x4*)(cp + g * 16 + 4);
;             *(f32x4*)&s[0] = *(const f32x4*)(sp + g * 16); *(f32x4*)&s[4] = *(const f32x4*)(sp + g * 16 + 4);
;             unpack8(*reinterpret_cast<const u32x4*>(Qw + (8 + g) * 16), x1); unpack8(*reinterpret_cast<const u32x4*>(Qw + (10 + g) * 16), x2);
; #pragma unroll
;             for (int j = 0; j < 8; ++j) { y1[j] = (x1[j] * c[j] - x2[j] * s[j]) * QC; y2[j] = (x2[j] * c[j] + x1[j] * s[j]) * QC; }
;             qr[8 + g] = __builtin_bit_cast(bf16x8, pack8(y1)); qr[10 + g] = __builtin_bit_cast(bf16x8, pack8(y2));
	v_lshlrev_b32_e32 v0, 16, v88
	v_and_b32_e32 v1, 0xffff0000, v88
	v_lshlrev_b32_e32 v4, 16, v89
	v_and_b32_e32 v5, 0xffff0000, v89
	v_lshlrev_b32_e32 v12, 16, v90
	v_and_b32_e32 v6, 0xffff0000, v90
	v_lshlrev_b32_e32 v13, 16, v91
	v_and_b32_e32 v7, 0xffff0000, v91
	v_mul_f32_e32 v4, 0x3dd53b94, v4
	v_mul_f32_e32 v5, 0x3dd53b94, v5
	v_mul_f32_e32 v6, 0x3dd53b94, v6
	v_mul_f32_e32 v7, 0x3dd53b94, v7
	v_mul_f32_e32 v0, 0x3dd53b94, v0
	v_mul_f32_e32 v1, 0x3dd53b94, v1
	v_mul_f32_e32 v12, 0x3dd53b94, v12
	v_mul_f32_e32 v13, 0x3dd53b94, v13
	v_cvt_pk_bf16_f32 v152, v0, v1
	v_cvt_pk_bf16_f32 v153, v4, v5
	v_cvt_pk_bf16_f32 v154, v12, v6
	v_cvt_pk_bf16_f32 v155, v13, v7
	s_waitcnt vmcnt(0)
	v_lshlrev_b32_e32 v0, 16, v92
	v_and_b32_e32 v1, 0xffff0000, v92
	v_mul_f32_e32 v0, 0x3dd53b94, v0
	v_lshlrev_b32_e32 v4, 16, v93
	v_and_b32_e32 v5, 0xffff0000, v93
	v_mul_f32_e32 v1, 0x3dd53b94, v1
	v_cvt_pk_bf16_f32 v156, v0, v1
	v_lshlrev_b32_e32 v0, 5, v11
	v_lshlrev_b32_e32 v12, 16, v94
	v_and_b32_e32 v6, 0xffff0000, v94
	v_lshlrev_b32_e32 v13, 16, v95
	v_and_b32_e32 v7, 0xffff0000, v95
	v_mul_f32_e32 v4, 0x3dd53b94, v4
	v_mul_f32_e32 v5, 0x3dd53b94, v5
	v_ashrrev_i32_e32 v1, 31, v0
	v_mul_f32_e32 v6, 0x3dd53b94, v6
	v_mul_f32_e32 v7, 0x3dd53b94, v7
	v_cvt_pk_bf16_f32 v157, v4, v5
	v_lshlrev_b64 v[4:5], 2, v[0:1]
	v_mul_f32_e32 v12, 0x3dd53b94, v12
	v_mul_f32_e32 v13, 0x3dd53b94, v13
	v_cvt_pk_bf16_f32 v158, v12, v6
	v_cvt_pk_bf16_f32 v159, v13, v7
	v_lshl_add_u64 v[6:7], s[72:73], 0, v[4:5]
	v_and_b32_e32 v0, 32, v9
	v_mov_b32_e32 v1, v185
	v_lshl_add_u64 v[32:33], v[6:7], 0, v[0:1]
	v_lshl_add_u64 v[4:5], s[70:71], 0, v[4:5]
	v_lshl_add_u64 v[34:35], v[4:5], 0, v[0:1]
	global_load_dwordx4 v[4:7], v[32:33], off offset:16
	global_load_dwordx4 v[12:15], v[32:33], off
	global_load_dwordx4 v[16:19], v[34:35], off offset:16
	global_load_dwordx4 v[20:23], v[34:35], off
	global_load_dwordx4 v[24:27], v[2:3], off offset:256
	global_load_dwordx4 v[28:31], v[2:3], off offset:320
	s_mov_b32 s70, 1
	s_mov_b32 s71, 0
	s_waitcnt vmcnt(4)
	v_mov_b32_e32 v38, v12
	s_waitcnt vmcnt(2)
	v_mov_b32_e32 v39, v20
	s_waitcnt vmcnt(1)
	v_lshlrev_b32_e32 v36, 16, v24
	s_waitcnt vmcnt(0)
	v_lshlrev_b32_e32 v37, 16, v28
	v_pk_mul_f32 v[38:39], v[38:39], v[36:37]
	s_nop 0
	v_sub_f32_e32 v1, v38, v39
	v_mov_b32_e32 v38, v20
	v_mov_b32_e32 v39, v12
	v_pk_mul_f32 v[36:37], v[38:39], v[36:37]
	v_mov_b32_e32 v20, v13
	v_add_f32_e32 v11, v36, v37
	v_and_b32_e32 v37, 0xffff0000, v28
	v_and_b32_e32 v36, 0xffff0000, v24
	v_pk_mul_f32 v[38:39], v[20:21], v[36:37]
	v_mov_b32_e32 v20, v14
	v_sub_f32_e32 v12, v38, v39
	v_mul_f32_e32 v24, 0x3dd53b94, v12
	v_mov_b32_e32 v12, v21
	v_pk_mul_f32 v[12:13], v[12:13], v[36:37]
	v_mov_b32_e32 v21, v22
	v_add_f32_e32 v12, v12, v13
	v_mul_f32_e32 v28, 0x3dd53b94, v12
	v_lshlrev_b32_e32 v13, 16, v29
	v_lshlrev_b32_e32 v12, 16, v25
	v_pk_mul_f32 v[20:21], v[20:21], v[12:13]
	v_mul_f32_e32 v1, 0x3dd53b94, v1
	v_sub_f32_e32 v20, v20, v21
	v_mul_f32_e32 v36, 0x3dd53b94, v20
	v_mov_b32_e32 v20, v22
	v_mov_b32_e32 v21, v14
	v_pk_mul_f32 v[12:13], v[20:21], v[12:13]
	v_mov_b32_e32 v22, v15
	v_add_f32_e32 v12, v12, v13
	v_mul_f32_e32 v37, 0x3dd53b94, v12
	v_and_b32_e32 v13, 0xffff0000, v29
	v_and_b32_e32 v12, 0xffff0000, v25
	v_pk_mul_f32 v[20:21], v[22:23], v[12:13]
	v_mul_f32_e32 v11, 0x3dd53b94, v11
	v_sub_f32_e32 v14, v20, v21
	v_mul_f32_e32 v20, 0x3dd53b94, v14
	v_mov_b32_e32 v14, v23
	v_pk_mul_f32 v[12:13], v[14:15], v[12:13]
	v_mov_b32_e32 v14, v4
	v_add_f32_e32 v12, v12, v13
	v_mul_f32_e32 v21, 0x3dd53b94, v12
	v_lshlrev_b32_e32 v13, 16, v30
	v_lshlrev_b32_e32 v12, 16, v26
	v_mov_b32_e32 v15, v16
	v_pk_mul_f32 v[14:15], v[14:15], v[12:13]
	v_cvt_pk_bf16_f32 v164, v1, v24
	v_cvt_pk_bf16_f32 v165, v36, v20
	s_nop 0
	v_sub_f32_e32 v14, v14, v15
	v_mul_f32_e32 v22, 0x3dd53b94, v14
	v_mov_b32_e32 v14, v16
	v_mov_b32_e32 v15, v4
	v_pk_mul_f32 v[12:13], v[14:15], v[12:13]
	v_mov_b32_e32 v16, v5
	v_add_f32_e32 v4, v12, v13
	v_and_b32_e32 v13, 0xffff0000, v30
	v_and_b32_e32 v12, 0xffff0000, v26
	v_pk_mul_f32 v[14:15], v[16:17], v[12:13]
	v_mul_f32_e32 v23, 0x3dd53b94, v4
	v_sub_f32_e32 v4, v14, v15
	v_mul_f32_e32 v14, 0x3dd53b94, v4
	v_mov_b32_e32 v4, v17
	v_pk_mul_f32 v[4:5], v[4:5], v[12:13]
	v_mov_b32_e32 v12, v6
	v_add_f32_e32 v4, v4, v5
	v_mul_f32_e32 v15, 0x3dd53b94, v4
	v_lshlrev_b32_e32 v5, 16, v31
	v_lshlrev_b32_e32 v4, 16, v27
	v_mov_b32_e32 v13, v18
	v_pk_mul_f32 v[12:13], v[12:13], v[4:5]
	v_cvt_pk_bf16_f32 v166, v22, v14
	s_nop 0
	v_sub_f32_e32 v12, v12, v13
	v_mul_f32_e32 v16, 0x3dd53b94, v12
	v_mov_b32_e32 v12, v18
	v_mov_b32_e32 v13, v6
	v_pk_mul_f32 v[4:5], v[12:13], v[4:5]
	v_mov_b32_e32 v18, v7
	v_add_f32_e32 v4, v4, v5
	v_mul_f32_e32 v17, 0x3dd53b94, v4
	v_and_b32_e32 v5, 0xffff0000, v31
	v_and_b32_e32 v4, 0xffff0000, v27
	v_pk_mul_f32 v[12:13], v[18:19], v[4:5]
	s_nop 0
	v_sub_f32_e32 v6, v12, v13
	v_mul_f32_e32 v12, 0x3dd53b94, v6
	v_mov_b32_e32 v6, v19
	v_pk_mul_f32 v[4:5], v[6:7], v[4:5]
	v_cvt_pk_bf16_f32 v167, v16, v12
	v_cvt_pk_bf16_f32 v160, v11, v28
	v_cvt_pk_bf16_f32 v161, v37, v21
	v_cvt_pk_bf16_f32 v162, v23, v15
	s_nop 0
	v_add_f32_e32 v4, v4, v5
	v_mul_f32_e32 v4, 0x3dd53b94, v4
	v_cvt_pk_bf16_f32 v163, v17, v4
	global_load_dwordx4 v[4:7], v[32:33], off offset:80
	global_load_dwordx4 v[12:15], v[32:33], off offset:64
	global_load_dwordx4 v[16:19], v[34:35], off offset:80
	global_load_dwordx4 v[20:23], v[34:35], off offset:64
	global_load_dwordx4 v[24:27], v[2:3], off offset:288
	global_load_dwordx4 v[28:31], v[2:3], off offset:352
	s_waitcnt vmcnt(4)
	v_mov_b32_e32 v32, v12
	s_waitcnt vmcnt(2)
	v_mov_b32_e32 v33, v20
	s_waitcnt vmcnt(1)
; __device__ __forceinline__ int v_rd_base(int lane) { return ((lane & 3) << 3) | (((lane >> 2) & 3) << 6) | (((lane >> 4) & 1) << 5) | (((lane >> 5) & 1) << 8); }
; #define DMA_V(t, slot) do { glds16(vsrc[0] + (long)(t) * 65536, (unsigned)__builtin_amdgcn_readfirstlane(vdst + (slot) * SHM_V)); \
;     glds16(vsrc[1] + (long)(t) * 65536, (unsigned)__builtin_amdgcn_readfirstlane(vdst + (slot) * SHM_V + 1024)); } while (0)
; __device__ __forceinline__ void attn_unit(const bf16_t* __restrict__ Qb, const bf16_t* __restrict__ Kh, const bf16_t* __restrict__ Vh, const bf16_t* __restrict__ Krh, ...
;     ...
;             *(f32x4*)&c[0] = *(const f32x4*)(cp + g * 16); *(f32x4*)&c[4] = *(const f32x4*)(cp + g * 16 + 4);
;             *(f32x4*)&s[0] = *(const f32x4*)(sp + g * 16); *(f32x4*)&s[4] = *(const f32x4*)(sp + g * 16 + 4);
;             unpack8(*reinterpret_cast<const u32x4*>(Qw + (8 + g) * 16), x1); unpack8(*reinterpret_cast<const u32x4*>(Qw + (10 + g) * 16), x2);
; #pragma unroll
;             for (int j = 0; j < 8; ++j) { y1[j] = (x1[j] * c[j] - x2[j] * s[j]) * QC; y2[j] = (x2[j] * c[j] + x1[j] * s[j]) * QC; }
;             qr[8 + g] = __builtin_bit_cast(bf16x8, pack8(y1)); qr[10 + g] = __builtin_bit_cast(bf16x8, pack8(y2));
;         }
;     }
;     const bf16_t* ksrc[2]; const bf16_t* vsrc[2]; const bf16_t* krsrc;
; #pragma unroll
;     for (int i = 0; i < 2; ++i) { const int p = (wid * 2 + i) * 64 + lane;
;         { const int row = p >> 4, c = (p & 15) ^ (row & 15); ksrc[i] = Kh + (long)row * 1024 + c * 8; }
;         { const int s = p >> 5, q = p & 31, kk = (s >> 2) * 8 + (q >> 2), k = (kk & ~0xC) | ((kk & 4) << 1) | ((kk & 8) >> 1), c = (s & 3) * 32 + (q & 3) * 8; vsrc[i] = Vh + (long)k * 1024 + c; } }
;     { const int p = wid * 64 + lane, row = p >> 3, c = (p & 7) ^ ((row >> 1) & 7); krsrc = Krh + (long)row * 64 + c * 8; }
;     const unsigned lds0 = (unsigned)(uintptr_t)lds;
;     const unsigned kdst = lds0 + OFF_K + wid * 2048, krdst = lds0 + OFF_KR + wid * 1024, vdst = lds0 + OFF_V + wid * 2048;
;     ...
;     const int vb0 = (int)(uintptr_t)V_lds + v_rd_base(lane);
;     const int NT = seq / 64;
;     ...
;     f32x16 p0, p1; float al = 1.f, mn_; bf16x8 pa0, pa1, pa2, pa3;
;     asm volatile("s_waitcnt vmcnt(0) lgkmcnt(0)" ::: "memory");
;     DMA_K(0, 0); DMA_V(0, 0); DMA_K(1, 1);
;     WAIT_BAR(0);
	v_lshlrev_b32_e32 v2, 16, v24
	s_waitcnt vmcnt(0)
	v_lshlrev_b32_e32 v3, 16, v28
	v_pk_mul_f32 v[32:33], v[32:33], v[2:3]
	s_nop 0
	v_sub_f32_e32 v1, v32, v33
	v_mov_b32_e32 v32, v20
	v_mov_b32_e32 v33, v12
	v_pk_mul_f32 v[2:3], v[32:33], v[2:3]
	v_mov_b32_e32 v20, v13
	v_add_f32_e32 v2, v2, v3
	v_mul_f32_e32 v11, 0x3dd53b94, v2
	v_and_b32_e32 v3, 0xffff0000, v28
	v_and_b32_e32 v2, 0xffff0000, v24
	v_pk_mul_f32 v[32:33], v[20:21], v[2:3]
	v_mul_f32_e32 v1, 0x3dd53b94, v1
	v_sub_f32_e32 v12, v32, v33
	v_mul_f32_e32 v20, 0x3dd53b94, v12
	v_mov_b32_e32 v12, v21
	v_pk_mul_f32 v[2:3], v[12:13], v[2:3]
	v_mov_b32_e32 v12, v14
	v_add_f32_e32 v2, v2, v3
	v_mul_f32_e32 v21, 0x3dd53b94, v2
	v_lshlrev_b32_e32 v3, 16, v29
	v_lshlrev_b32_e32 v2, 16, v25
	v_mov_b32_e32 v13, v22
	v_pk_mul_f32 v[12:13], v[12:13], v[2:3]
	v_cvt_pk_bf16_f32 v172, v1, v20
	v_lshlrev_b32_e32 v1, 7, v10
	v_sub_f32_e32 v12, v12, v13
	v_mul_f32_e32 v24, 0x3dd53b94, v12
	v_mov_b32_e32 v12, v22
	v_mov_b32_e32 v13, v14
	v_pk_mul_f32 v[2:3], v[12:13], v[2:3]
	v_mov_b32_e32 v22, v15
	v_add_f32_e32 v2, v2, v3
	v_mul_f32_e32 v28, 0x3dd53b94, v2
	v_and_b32_e32 v3, 0xffff0000, v29
	v_and_b32_e32 v2, 0xffff0000, v25
	v_mov_b32_e32 v14, v23
	v_pk_mul_f32 v[12:13], v[22:23], v[2:3]
	v_pk_mul_f32 v[2:3], v[14:15], v[2:3]
	v_sub_f32_e32 v12, v12, v13
	v_add_f32_e32 v2, v2, v3
	v_mul_f32_e32 v22, 0x3dd53b94, v12
	v_mul_f32_e32 v14, 0x3dd53b94, v2
	v_lshlrev_b32_e32 v3, 16, v30
	v_lshlrev_b32_e32 v2, 16, v26
	v_mov_b32_e32 v12, v4
	v_mov_b32_e32 v13, v16
	v_pk_mul_f32 v[12:13], v[12:13], v[2:3]
	v_cvt_pk_bf16_f32 v173, v24, v22
	s_nop 0
	v_sub_f32_e32 v12, v12, v13
	v_mul_f32_e32 v15, 0x3dd53b94, v12
	v_mov_b32_e32 v12, v16
	v_mov_b32_e32 v13, v4
	v_pk_mul_f32 v[2:3], v[12:13], v[2:3]
	v_mov_b32_e32 v16, v5
	v_add_f32_e32 v2, v2, v3
	v_mul_f32_e32 v23, 0x3dd53b94, v2
	v_and_b32_e32 v3, 0xffff0000, v30
	v_and_b32_e32 v2, 0xffff0000, v26
	v_pk_mul_f32 v[12:13], v[16:17], v[2:3]
	s_nop 0
	v_sub_f32_e32 v4, v12, v13
	v_mul_f32_e32 v12, 0x3dd53b94, v4
	v_mov_b32_e32 v4, v17
	v_pk_mul_f32 v[2:3], v[4:5], v[2:3]
	v_mov_b32_e32 v4, v6
	v_add_f32_e32 v2, v2, v3
	v_mul_f32_e32 v13, 0x3dd53b94, v2
	v_lshlrev_b32_e32 v3, 16, v31
	v_lshlrev_b32_e32 v2, 16, v27
	v_mov_b32_e32 v5, v18
	v_pk_mul_f32 v[4:5], v[4:5], v[2:3]
	v_cvt_pk_bf16_f32 v174, v15, v12
	v_or_b32_e32 v12, v1, v8
	v_sub_f32_e32 v4, v4, v5
	v_mul_f32_e32 v16, 0x3dd53b94, v4
	v_mov_b32_e32 v4, v18
	v_mov_b32_e32 v5, v6
	v_pk_mul_f32 v[2:3], v[4:5], v[2:3]
	v_mov_b32_e32 v18, v7
	v_add_f32_e32 v2, v2, v3
	v_mul_f32_e32 v17, 0x3dd53b94, v2
	v_and_b32_e32 v3, 0xffff0000, v31
	v_and_b32_e32 v2, 0xffff0000, v27
	v_mov_b32_e32 v6, v19
	v_pk_mul_f32 v[4:5], v[18:19], v[2:3]
	v_pk_mul_f32 v[2:3], v[6:7], v[2:3]
	v_sub_f32_e32 v4, v4, v5
	v_add_f32_e32 v2, v2, v3
	v_mul_f32_e32 v4, 0x3dd53b94, v4
	v_mul_f32_e32 v2, 0x3dd53b94, v2
	v_ashrrev_i32_e32 v1, 4, v1
	v_cvt_pk_bf16_f32 v175, v16, v4
	v_cvt_pk_bf16_f32 v168, v11, v21
	v_cvt_pk_bf16_f32 v169, v28, v14
	v_cvt_pk_bf16_f32 v170, v23, v13
	v_cvt_pk_bf16_f32 v171, v17, v2
	v_bfe_u32 v2, v9, 2, 2
	v_and_b32_e32 v3, -16, v1
	v_lshrrev_b32_e32 v4, 1, v9
	v_lshrrev_b32_e32 v1, 1, v1
	v_and_b32_e32 v1, 4, v1
	v_and_or_b32 v2, v4, 8, v2
	v_ashrrev_i32_e32 v4, 4, v12
	v_or3_b32 v2, v2, v3, v1
	v_lshlrev_b32_e32 v1, 3, v9
	v_xor_b32_e32 v6, v4, v9
	v_ashrrev_i32_e32 v5, 31, v4
	v_and_b32_e32 v11, 24, v1
	v_ashrrev_i32_e32 v3, 31, v2
	v_lshlrev_b64 v[4:5], 11, v[4:5]
	v_lshlrev_b32_e32 v6, 4, v6
	v_lshlrev_b64 v[2:3], 11, v[2:3]
	v_lshl_add_u64 v[4:5], s[68:69], 0, v[4:5]
	v_and_b32_e32 v6, 0xf0, v6
	v_mov_b32_e32 v7, v185
	v_or_b32_e32 v0, v11, v0
	v_lshl_add_u64 v[2:3], s[68:69], 0, v[2:3]
	v_lshl_add_u64 v[188:189], v[4:5], 0, v[6:7]
	v_lshlrev_b32_e32 v4, 1, v0
	v_mov_b32_e32 v5, v185
	v_or_b32_e32 v0, 64, v12
	v_lshl_add_u64 v[76:77], v[2:3], 0, v[4:5]
	v_ashrrev_i32_e32 v4, 4, v0
	v_xor_b32_e32 v6, v4, v9
	v_ashrrev_i32_e32 v5, 31, v4
	v_lshlrev_b64 v[4:5], 11, v[4:5]
	v_lshlrev_b32_e32 v6, 4, v6
	v_lshl_add_u64 v[4:5], s[68:69], 0, v[4:5]
	v_and_b32_e32 v6, 0xf0, v6
	v_and_or_b32 v0, v0, s81, v11
	v_lshl_add_u64 v[190:191], v[4:5], 0, v[6:7]
	v_lshlrev_b32_e32 v4, 1, v0
	v_mov_b32_e32 v5, v185
	v_lshl_add_u64 v[78:79], v[2:3], 0, v[4:5]
	v_ashrrev_i32_e32 v2, 3, v9
	v_lshrrev_b32_e32 v0, 4, v9
	v_xor_b32_e32 v0, v0, v9
	v_ashrrev_i32_e32 v3, 31, v2
	v_lshlrev_b64 v[2:3], 7, v[2:3]
	v_lshlrev_b32_e32 v0, 4, v0
	v_lshl_add_u64 v[2:3], s[0:1], 0, v[2:3]
	v_and_b32_e32 v4, 0x70, v0
	v_lshlrev_b32_e32 v0, 11, v10
	v_lshl_add_u64 v[192:193], v[2:3], 0, v[4:5]
	v_add_u32_e32 v213, s10, v0
	v_lshlrev_b32_e32 v4, 10, v10
	s_add_i32 s0, s10, 0xc000
	v_add_u32_e32 v212, s0, v4
	s_waitcnt vmcnt(0) lgkmcnt(0)
	v_readfirstlane_b32 s0, v213
	s_mov_b32 s1, m0
	s_mov_b32 m0, s0
	s_nop 0
	global_load_lds_dwordx4 v[188:189], off
	s_mov_b32 m0, s1
	v_readfirstlane_b32 s0, v0
	s_add_i32 s6, s10, s0
	s_add_i32 s0, s6, 0x400
	v_add_u32_e32 v228, s7, v0
	s_mov_b32 s1, m0
	s_mov_b32 m0, s0
	s_nop 0
	global_load_lds_dwordx4 v[190:191], off
	s_mov_b32 m0, s1
	v_readfirstlane_b32 s0, v212
	s_mov_b32 s1, m0
	s_mov_b32 m0, s0
	s_nop 0
	global_load_lds_dwordx4 v[192:193], off
	s_mov_b32 m0, s1
	v_readfirstlane_b32 s0, v228
	v_lshl_add_u64 v[194:195], v[76:77], 0, s[30:31]
	s_mov_b32 s1, m0
	s_mov_b32 m0, s0
	s_nop 0
	global_load_lds_dwordx4 v[194:195], off
	s_mov_b32 m0, s1
	s_add_i32 s0, s6, 0x12400
	v_lshl_add_u64 v[196:197], v[78:79], 0, s[30:31]
	s_mov_b32 s1, m0
	s_mov_b32 m0, s0
	s_nop 0
	global_load_lds_dwordx4 v[196:197], off
	s_mov_b32 m0, s1
	s_add_i32 s0, s6, 0x4000
	v_lshl_add_u64 v[2:3], v[188:189], 0, s[36:37]
	s_mov_b32 s1, m0
	s_mov_b32 m0, s0
	s_nop 0
	global_load_lds_dwordx4 v[2:3], off
	s_mov_b32 m0, s1
	s_add_i32 s0, s6, 0x4400
	v_lshl_add_u64 v[2:3], v[190:191], 0, s[36:37]
	s_mov_b32 s1, m0
	s_mov_b32 m0, s0
	s_nop 0
	global_load_lds_dwordx4 v[2:3], off
	s_mov_b32 m0, s1
	v_readfirstlane_b32 s0, v4
	s_add_i32 s10, s10, s0
	s_add_i32 s0, s10, 0xe000
	v_lshlrev_b32_e32 v0, 1, v9
	v_lshl_add_u64 v[2:3], v[192:193], 0, s[38:39]
	s_mov_b32 s1, m0
	s_mov_b32 m0, s0
	s_nop 0
	global_load_lds_dwordx4 v[2:3], off
	s_mov_b32 m0, s1
	v_and_b32_e32 v0, 32, v0
	s_movk_i32 s0, 0x118
	v_and_or_b32 v0, v1, s0, v0
	v_lshlrev_b32_e32 v4, 4, v9
	s_movk_i32 s0, 0xf0
	v_and_b32_e32 v2, 0xc0, v4
	v_and_b32_e32 v3, 0xf0, v4
	v_bitop3_b32 v227, v184, v4, s0 bitop3:0x78
	s_movk_i32 s0, 0x70
	s_waitcnt vmcnt(0) lgkmcnt(0)
	s_barrier
; #define DMA_K(t, slot) do { glds16(ksrc[0] + (long)(t) * 65536, (unsigned)__builtin_amdgcn_readfirstlane(kdst + (slot) * SHM_K)); \
;     glds16(ksrc[1] + (long)(t) * 65536, (unsigned)__builtin_amdgcn_readfirstlane(kdst + (slot) * SHM_K + 1024)); \
;     glds16(krsrc + (long)(t) * 4096, (unsigned)__builtin_amdgcn_readfirstlane(krdst + (slot) * SHM_KR)); } while (0)
; #define DMA_V(t, slot) do { glds16(vsrc[0] + (long)(t) * 65536, (unsigned)__builtin_amdgcn_readfirstlane(vdst + (slot) * SHM_V)); \
;     glds16(vsrc[1] + (long)(t) * 65536, (unsigned)__builtin_amdgcn_readfirstlane(vdst + (slot) * SHM_V + 1024)); } while (0)
; __device__ __forceinline__ void qkt(f32x16& p0, f32x16& p1, const char* Ks, const char* Krs, const bf16x8* qr, const char* qro, int r32, int hi, const f32x16& negm) {
;     p0 = negm; p1 = negm;
; #pragma unroll
;     for (int d0 = 0; d0 < 8; ++d0) { const int cb = (d0 * 16 + hi * 8) * 2;
;         const bf16x8 b0 = *reinterpret_cast<const bf16x8*>(Ks + KSWZ(r32, cb));
;         const bf16x8 b1 = *reinterpret_cast<const bf16x8*>(Ks + KSWZ(32 + r32, cb));
;         p0 = __builtin_amdgcn_mfma_f32_32x32x16_bf16(b0, qr[d0], p0, 0, 0, 0);
;         p1 = __builtin_amdgcn_mfma_f32_32x32x16_bf16(b1, qr[d0], p1, 0, 0, 0); }
; #pragma unroll
;     for (int d0 = 0; d0 < 4; ++d0) { const int cb = (d0 * 16 + hi * 8) * 2;
;         const bf16x8 b0 = *reinterpret_cast<const bf16x8*>(Krs + KRSWZ(r32, cb));
;         const bf16x8 b1 = *reinterpret_cast<const bf16x8*>(Krs + KRSWZ(32 + r32, cb));
;         const bf16x8 qf = qr[8 + d0];
;         p0 = __builtin_amdgcn_mfma_f32_32x32x16_bf16(b0, qf, p0, 0, 0, 0);
;         p1 = __builtin_amdgcn_mfma_f32_32x32x16_bf16(b1, qf, p1, 0, 0, 0); }
; __device__ __forceinline__ void attn_unit(const bf16_t* __restrict__ Qb, const bf16_t* __restrict__ Kh, const bf16_t* __restrict__ Vh, const bf16_t* __restrict__ Krh, ...
;     ...
;         if (j + 1 < NT) DMA_V(j + 1, s2);
;         if (j + 2 < NT) DMA_K(j + 2, s0);
	v_bitop3_b32 v226, v184, v3, 32 bitop3:0x36
	v_bitop3_b32 v225, v184, v3, 64 bitop3:0x36
	v_bitop3_b32 v224, v184, v3, s81 bitop3:0x36
	v_bitop3_b32 v223, v184, v3, s83 bitop3:0x36
	v_bitop3_b32 v222, v184, v3, s90 bitop3:0x36
	v_bitop3_b32 v221, v184, v3, s82 bitop3:0x36
	v_bitop3_b32 v220, v184, v3, s91 bitop3:0x36
	v_and_b32_e32 v3, 0x70, v1
	v_bitop3_b32 v219, v184, v1, s0 bitop3:0x78
	v_add3_u32 v214, v2, s7, v0
	v_lshl_add_u64 v[0:1], v[76:77], 0, s[40:41]
	s_add_i32 s7, s6, 0x16000
	s_mov_b32 s11, m0
	s_mov_b32 m0, s7
	s_nop 0
	global_load_lds_dwordx4 v[0:1], off
	s_mov_b32 m0, s11
	v_lshl_add_u64 v[0:1], v[78:79], 0, s[40:41]
	s_add_i32 s7, s6, 0x16400
	s_mov_b32 s11, m0
	s_mov_b32 m0, s7
	s_nop 0
	global_load_lds_dwordx4 v[0:1], off
	s_mov_b32 m0, s11
	v_lshl_add_u64 v[0:1], v[188:189], 0, s[42:43]
	s_add_i32 s7, s6, 0x8000
	s_mov_b32 s11, m0
	s_mov_b32 m0, s7
	s_nop 0
	global_load_lds_dwordx4 v[0:1], off
	s_mov_b32 m0, s11
	v_lshl_add_u64 v[0:1], v[190:191], 0, s[42:43]
	s_add_i32 s6, s6, 0x8400
	s_mov_b32 s7, m0
	s_mov_b32 m0, s6
	s_nop 0
	global_load_lds_dwordx4 v[0:1], off
	s_mov_b32 m0, s7
	v_lshl_add_u64 v[0:1], v[192:193], 0, s[44:45]
	s_add_i32 s10, s10, 0x10000
	s_mov_b32 s6, m0
	s_mov_b32 m0, s10
	s_nop 0
	global_load_lds_dwordx4 v[0:1], off
	s_mov_b32 m0, s6
	v_add3_u32 v0, 0, v227, v211
	v_bitop3_b32 v218, v184, v3, 32 bitop3:0x36
	v_bitop3_b32 v217, v184, v3, 64 bitop3:0x36
	v_bitop3_b32 v216, v184, v3, s81 bitop3:0x36
	ds_read_b128 v[2:5], v0
	ds_read_b128 v[16:19], v0 offset:8192
	v_cmp_gt_u32_e64 s[0:1], 32, v8
	s_waitcnt lgkmcnt(1)
	v_mfma_f32_32x32x16_bf16 v[0:15], v[2:5], v[128:131], 0
	v_add3_u32 v36, 0, v226, v211
	ds_read_b128 v[32:35], v36
	ds_read_b128 v[36:39], v36 offset:8192
	s_waitcnt lgkmcnt(2)
	v_mfma_f32_32x32x16_bf16 v[16:31], v[16:19], v[128:131], 0
	s_waitcnt lgkmcnt(1)
	v_mfma_f32_32x32x16_bf16 v[0:15], v[32:35], v[132:135], v[0:15]
	s_waitcnt lgkmcnt(0)
	v_mfma_f32_32x32x16_bf16 v[16:31], v[36:39], v[132:135], v[16:31]
	v_add3_u32 v36, 0, v225, v211
	ds_read_b128 v[32:35], v36
	ds_read_b128 v[36:39], v36 offset:8192
	s_waitcnt lgkmcnt(1)
	v_mfma_f32_32x32x16_bf16 v[0:15], v[32:35], v[136:139], v[0:15]
	s_waitcnt lgkmcnt(0)
	v_mfma_f32_32x32x16_bf16 v[16:31], v[36:39], v[136:139], v[16:31]
	v_add3_u32 v36, 0, v224, v211
	ds_read_b128 v[32:35], v36
	ds_read_b128 v[36:39], v36 offset:8192
	s_waitcnt lgkmcnt(1)
	v_mfma_f32_32x32x16_bf16 v[0:15], v[32:35], v[140:143], v[0:15]
	s_waitcnt lgkmcnt(0)
	v_mfma_f32_32x32x16_bf16 v[16:31], v[36:39], v[140:143], v[16:31]
	v_add3_u32 v36, 0, v223, v211
	ds_read_b128 v[32:35], v36
	ds_read_b128 v[36:39], v36 offset:8192
	s_waitcnt lgkmcnt(1)
	v_mfma_f32_32x32x16_bf16 v[0:15], v[32:35], v[144:147], v[0:15]
	s_waitcnt lgkmcnt(0)
	v_mfma_f32_32x32x16_bf16 v[16:31], v[36:39], v[144:147], v[16:31]
	v_add3_u32 v36, 0, v222, v211
	ds_read_b128 v[32:35], v36
	ds_read_b128 v[36:39], v36 offset:8192
	s_waitcnt lgkmcnt(1)
	v_mfma_f32_32x32x16_bf16 v[0:15], v[32:35], v[148:151], v[0:15]
	s_waitcnt lgkmcnt(0)
	v_mfma_f32_32x32x16_bf16 v[16:31], v[36:39], v[148:151], v[16:31]
	v_add3_u32 v36, 0, v221, v211
	ds_read_b128 v[32:35], v36
	ds_read_b128 v[36:39], v36 offset:8192
	s_waitcnt lgkmcnt(1)
	v_mfma_f32_32x32x16_bf16 v[0:15], v[32:35], v[152:155], v[0:15]
	s_waitcnt lgkmcnt(0)
	v_mfma_f32_32x32x16_bf16 v[16:31], v[36:39], v[152:155], v[16:31]
	v_add3_u32 v36, 0, v220, v211
	ds_read_b128 v[32:35], v36
	ds_read_b128 v[36:39], v36 offset:8192
	s_waitcnt lgkmcnt(1)
	v_mfma_f32_32x32x16_bf16 v[0:15], v[32:35], v[156:159], v[0:15]
	s_waitcnt lgkmcnt(0)
	v_mfma_f32_32x32x16_bf16 v[16:31], v[36:39], v[156:159], v[16:31]
	v_add3_u32 v36, 0, v219, v215
	ds_read_b128 v[32:35], v36 offset:49152
	ds_read_b128 v[36:39], v36 offset:53248
	s_waitcnt lgkmcnt(1)
	v_mfma_f32_32x32x16_bf16 v[0:15], v[32:35], v[164:167], v[0:15]
	s_waitcnt lgkmcnt(0)
	v_mfma_f32_32x32x16_bf16 v[16:31], v[36:39], v[164:167], v[16:31]
	v_add3_u32 v36, 0, v218, v215
	ds_read_b128 v[32:35], v36 offset:49152
	ds_read_b128 v[36:39], v36 offset:53248
	s_waitcnt lgkmcnt(1)
	v_mfma_f32_32x32x16_bf16 v[0:15], v[32:35], v[172:175], v[0:15]
	s_waitcnt lgkmcnt(0)
	v_mfma_f32_32x32x16_bf16 v[16:31], v[36:39], v[172:175], v[16:31]
	v_add3_u32 v36, 0, v217, v215
	ds_read_b128 v[32:35], v36 offset:49152
	ds_read_b128 v[36:39], v36 offset:53248
	s_waitcnt lgkmcnt(1)
	v_mfma_f32_32x32x16_bf16 v[0:15], v[32:35], v[160:163], v[0:15]
	s_waitcnt lgkmcnt(0)
	v_mfma_f32_32x32x16_bf16 v[16:31], v[36:39], v[160:163], v[16:31]
	v_add3_u32 v36, 0, v216, v215
	ds_read_b128 v[32:35], v36 offset:49152
	ds_read_b128 v[36:39], v36 offset:53248
	s_waitcnt lgkmcnt(1)
	v_mfma_f32_32x32x16_bf16 v[0:15], v[32:35], v[168:171], v[0:15]
	s_waitcnt lgkmcnt(0)
; __device__ __forceinline__ void partialSM(f32x16& p0, f32x16& p1, float& m_ref, f32x16& negm, float& alpha, bool first) {
;     constexpr float THR2 = THR * 1.4426950408889634f;
;     float ma = p0[0], mb = p0[8], mc = p1[0], md = p1[8];
; #pragma unroll
;     for (int r = 1; r < 8; ++r) { ma = fmaxf(ma, p0[r]); mb = fmaxf(mb, p0[8 + r]); mc = fmaxf(mc, p1[r]); md = fmaxf(md, p1[8 + r]); }
;     float pmax = fmaxf(fmaxf(ma, mb), fmaxf(mc, md));
;     { auto rr = __builtin_amdgcn_permlane32_swap(__float_as_uint(pmax), __float_as_uint(pmax), false, false);
;       pmax = fmaxf(__uint_as_float(rr[0]), __uint_as_float(rr[1])); }
;     if (__builtin_expect(!first && __all(pmax <= THR2), 1)) { alpha = 1.f; }
;     else { const float d = first ? pmax : fmaxf(pmax, 0.f); m_ref += d; alpha = first ? 1.f : __builtin_amdgcn_exp2f(-d);
; #pragma unroll
;         for (int r = 0; r < 16; ++r) { p0[r] -= d; p1[r] -= d; }
; #pragma unroll
;         for (int r = 0; r < 16; ++r) negm[r] = -m_ref; }
; #pragma unroll
;     for (int r = 0; r < 16; ++r) p0[r] = __builtin_amdgcn_exp2f(p0[r]);
; }
; __device__ __forceinline__ void finishSM(f32x16& p0, f32x16& p1, float alpha, float& l_reg, bf16x8& pa0, bf16x8& pa1, bf16x8& pa2, bf16x8& pa3) {
; #pragma unroll
;     for (int r = 0; r < 16; ++r) p1[r] = __builtin_amdgcn_exp2f(p1[r]);
;     float sa = p0[0], sb = p0[8], sc = p1[0], sd = p1[8];
; #pragma unroll
;     for (int r = 1; r < 8; ++r) { sa += p0[r]; sb += p0[8 + r]; sc += p1[r]; sd += p1[8 + r]; }
;     float ps = (sa + sb) + (sc + sd);
;     { auto rr = __builtin_amdgcn_permlane32_swap(__float_as_uint(ps), __float_as_uint(ps), false, false);
;       ps = __uint_as_float(rr[0]) + __uint_as_float(rr[1]); }
;     l_reg = l_reg * alpha + ps;
;     ...
;     PK4(p0, 0, pa0); PK4(p0, 8, pa1); PK4(p1, 0, pa2); PK4(p1, 8, pa3);
;     ...
; }
; template <int D0> __device__ __forceinline__ void pv_one(f32x16& od, int vb, bf16x8 pa0, bf16x8 pa1, bf16x8 pa2, bf16x8 pa3) {
;     const s16x4 l0 = tr_read<v_rd_off(D0, 0, 0)>(vb), h0 = tr_read<v_rd_off(D0, 0, 1)>(vb), l1 = tr_read<v_rd_off(D0, 1, 0)>(vb), h1 = tr_read<v_rd_off(D0, 1, 1)>(vb);
;     const s16x4 l2 = tr_read<v_rd_off(D0, 2, 0)>(vb), h2 = tr_read<v_rd_off(D0, 2, 1)>(vb), l3 = tr_read<v_rd_off(D0, 3, 0)>(vb), h3 = tr_read<v_rd_off(D0, 3, 1)>(vb);
;     asm volatile("s_waitcnt lgkmcnt(0)" ::: "memory"); SBAR();
	v_mfma_f32_32x32x16_bf16 v[16:31], v[36:39], v[168:171], v[16:31]
	s_nop 9
	v_max_f32_e32 v32, v1, v1
	v_max_f32_e32 v33, v0, v0
	v_max_f32_e32 v32, v33, v32
	v_max_f32_e32 v33, v9, v9
	v_max_f32_e32 v34, v8, v8
	v_max_f32_e32 v33, v34, v33
	v_max3_f32 v32, v32, v2, v3
	v_max_f32_e32 v34, v25, v25
	v_max_f32_e32 v35, v24, v24
	v_max_f32_e32 v34, v35, v34
	v_max3_f32 v35, v16, v17, v18
	v_max3_f32 v34, v34, v26, v27
	v_max3_f32 v33, v33, v10, v11
	v_max3_f32 v35, v35, v19, v20
	v_max3_f32 v34, v34, v28, v29
	v_max3_f32 v32, v32, v4, v5
	v_max3_f32 v33, v33, v12, v13
	v_max3_f32 v35, v35, v21, v22
	v_max3_f32 v34, v34, v30, v31
	v_max3_f32 v32, v32, v6, v7
	v_max3_f32 v33, v33, v14, v15
	v_max3_f32 v34, v35, v23, v34
	v_max3_f32 v32, v32, v33, v34
	v_mov_b32_e32 v33, v32
	s_nop 1
	v_permlane32_swap_b32_e32 v32, v33
	v_max_f32_e32 v33, v33, v33
	v_max_f32_e32 v32, v32, v32
	v_max_f32_e32 v33, v32, v33
	v_sub_f32_e32 v32, v16, v33
	v_sub_f32_e32 v17, v17, v33
	v_sub_f32_e32 v34, v18, v33
	v_sub_f32_e32 v19, v19, v33
	v_sub_f32_e32 v36, v22, v33
	v_sub_f32_e32 v37, v24, v33
	v_sub_f32_e32 v25, v25, v33
	v_sub_f32_e32 v0, v0, v33
	v_sub_f32_e32 v1, v1, v33
	v_sub_f32_e32 v16, v2, v33
	v_sub_f32_e32 v3, v3, v33
	v_sub_f32_e32 v18, v4, v33
	v_sub_f32_e32 v7, v7, v33
	v_sub_f32_e32 v22, v8, v33
	v_sub_f32_e32 v9, v9, v33
	v_sub_f32_e32 v35, v20, v33
	v_sub_f32_e32 v21, v21, v33
	v_sub_f32_e32 v38, v26, v33
	v_sub_f32_e32 v39, v28, v33
	v_sub_f32_e32 v5, v5, v33
	v_sub_f32_e32 v20, v6, v33
	v_sub_f32_e32 v24, v10, v33
	v_sub_f32_e32 v11, v11, v33
	v_sub_f32_e32 v28, v14, v33
	v_exp_f32_e32 v0, v0
	v_exp_f32_e32 v2, v1
	v_exp_f32_e32 v4, v16
	v_exp_f32_e32 v6, v3
	v_exp_f32_e32 v8, v18
	v_exp_f32_e32 v14, v7
	v_exp_f32_e32 v16, v22
	v_exp_f32_e32 v18, v9
	v_exp_f32_e32 v1, v32
	v_exp_f32_e32 v3, v17
	v_exp_f32_e32 v7, v19
	v_exp_f32_e32 v19, v37
	v_exp_f32_e32 v17, v25
	v_sub_f32_e32 v23, v23, v33
	v_sub_f32_e32 v27, v27, v33
	v_sub_f32_e32 v26, v12, v33
	v_sub_f32_e32 v15, v15, v33
	v_exp_f32_e32 v10, v5
	v_exp_f32_e32 v12, v20
	v_exp_f32_e32 v20, v24
	v_exp_f32_e32 v22, v11
	v_exp_f32_e32 v5, v34
	v_exp_f32_e32 v11, v21
	v_exp_f32_e32 v21, v38
	v_sub_f32_e32 v40, v30, v33
	v_exp_f32_e32 v30, v15
	v_exp_f32_e32 v15, v23
	v_exp_f32_e32 v23, v27
	v_sub_f32_e32 v29, v29, v33
	v_sub_f32_e32 v13, v13, v33
	v_exp_f32_e32 v24, v26
	v_exp_f32_e32 v9, v35
	v_exp_f32_e32 v25, v39
	v_exp_f32_e32 v26, v13
	v_exp_f32_e32 v13, v36
	v_exp_f32_e32 v27, v29
	v_pk_add_f32 v[34:35], v[2:3], v[0:1]
	v_pk_add_f32 v[36:37], v[18:19], v[16:17]
	v_sub_f32_e32 v31, v31, v33
	v_exp_f32_e32 v28, v28
	v_exp_f32_e32 v29, v40
	v_pk_add_f32 v[34:35], v[4:5], v[34:35]
	v_pk_add_f32 v[36:37], v[20:21], v[36:37]
	v_exp_f32_e32 v31, v31
	v_pk_add_f32 v[34:35], v[6:7], v[34:35]
	v_pk_add_f32 v[36:37], v[22:23], v[36:37]
	v_pk_add_f32 v[34:35], v[8:9], v[34:35]
	v_pk_add_f32 v[36:37], v[24:25], v[36:37]
	v_cvt_pk_bf16_f32 v48, v0, v2
	v_cvt_pk_bf16_f32 v49, v4, v6
	v_cvt_pk_bf16_f32 v50, v8, v10
	v_cvt_pk_bf16_f32 v51, v12, v14
	v_cvt_pk_bf16_f32 v68, v16, v18
	v_cvt_pk_bf16_f32 v69, v20, v22
	v_cvt_pk_bf16_f32 v70, v24, v26
	v_cvt_pk_bf16_f32 v71, v28, v30
	v_cvt_pk_bf16_f32 v64, v1, v3
	v_cvt_pk_bf16_f32 v65, v5, v7
	v_cvt_pk_bf16_f32 v66, v9, v11
	v_cvt_pk_bf16_f32 v67, v13, v15
	v_cvt_pk_bf16_f32 v72, v19, v17
	v_cvt_pk_bf16_f32 v73, v21, v23
	v_cvt_pk_bf16_f32 v74, v25, v27
	v_cvt_pk_bf16_f32 v75, v29, v31
	ds_read_b64_tr_b16 v[0:1], v214 offset:0
	v_pk_add_f32 v[34:35], v[10:11], v[34:35]
	v_pk_add_f32 v[36:37], v[26:27], v[36:37]
	ds_read_b64_tr_b16 v[2:3], v214 offset:0x800
	v_pk_add_f32 v[34:35], v[12:13], v[34:35]
	v_pk_add_f32 v[36:37], v[28:29], v[36:37]
	ds_read_b64_tr_b16 v[16:17], v214 offset:0x1000
	v_pk_add_f32 v[34:35], v[14:15], v[34:35]
	v_pk_add_f32 v[36:37], v[30:31], v[36:37]
	ds_read_b64_tr_b16 v[18:19], v214 offset:0x1800
	ds_read_b64_tr_b16 v[20:21], v214 offset:0x2000
	ds_read_b64_tr_b16 v[22:23], v214 offset:0x2800
	ds_read_b64_tr_b16 v[24:25], v214 offset:0x3000
	ds_read_b64_tr_b16 v[26:27], v214 offset:0x3800
	s_nop 0
	v_pk_add_f32 v[34:35], v[36:37], v[34:35]
	s_waitcnt lgkmcnt(0)
	v_permlane32_swap_b32_e32 v48, v50
	v_pk_add_f32 v[34:35], v[34:35], v[34:35] op_sel:[0,1] op_sel_hi:[1,0]
	v_permlane32_swap_b32_e32 v49, v51
	v_mov_b32_e32 v32, v34
	s_nop 1
	v_permlane32_swap_b32_e32 v34, v32
	v_add_f32_e32 v32, v34, v32
	v_pk_add_f32 v[198:199], v[32:33], 0 op_sel_hi:[1,0]
	v_permlane32_swap_b32_e32 v68, v70
	v_xor_b32_e32 v80, 0x80000000, v199
	v_permlane32_swap_b32_e32 v69, v71
	v_permlane32_swap_b32_e32 v64, v66
	v_permlane32_swap_b32_e32 v65, v67
	v_permlane32_swap_b32_e32 v72, v74
	v_permlane32_swap_b32_e32 v73, v75
	v_mfma_f32_32x32x16_bf16 v[0:15], v[48:51], v[0:3], 0
	v_mfma_f32_32x32x16_bf16 v[0:15], v[68:71], v[16:19], v[0:15]
	ds_read_b64_tr_b16 v[16:17], v214 offset:0x200
	ds_read_b64_tr_b16 v[18:19], v214 offset:0xa00
	ds_read_b64_tr_b16 v[32:33], v214 offset:0x1200
	ds_read_b64_tr_b16 v[34:35], v214 offset:0x1a00
	ds_read_b64_tr_b16 v[36:37], v214 offset:0x2200
	ds_read_b64_tr_b16 v[38:39], v214 offset:0x2a00
	ds_read_b64_tr_b16 v[40:41], v214 offset:0x3200
	v_mfma_f32_32x32x16_bf16 v[0:15], v[64:67], v[20:23], v[0:15]
	ds_read_b64_tr_b16 v[42:43], v214 offset:0x3a00
	s_waitcnt lgkmcnt(0)
	v_mfma_f32_32x32x16_bf16 v[0:15], v[72:75], v[24:27], v[0:15]
	v_mfma_f32_32x32x16_bf16 v[16:31], v[48:51], v[16:19], 0
	v_mfma_f32_32x32x16_bf16 v[16:31], v[68:71], v[32:35], v[16:31]
	ds_read_b64_tr_b16 v[32:33], v214 offset:0x400
	ds_read_b64_tr_b16 v[34:35], v214 offset:0xc00
	ds_read_b64_tr_b16 v[52:53], v214 offset:0x1400
	ds_read_b64_tr_b16 v[54:55], v214 offset:0x1c00
	ds_read_b64_tr_b16 v[56:57], v214 offset:0x2400
	ds_read_b64_tr_b16 v[58:59], v214 offset:0x2c00
	ds_read_b64_tr_b16 v[60:61], v214 offset:0x3400
	v_mfma_f32_32x32x16_bf16 v[16:31], v[64:67], v[36:39], v[16:31]
	ds_read_b64_tr_b16 v[62:63], v214 offset:0x3c00
	s_waitcnt lgkmcnt(0)
	v_mfma_f32_32x32x16_bf16 v[16:31], v[72:75], v[40:43], v[16:31]
	v_mfma_f32_32x32x16_bf16 v[32:47], v[48:51], v[32:35], 0
	v_mfma_f32_32x32x16_bf16 v[32:47], v[68:71], v[52:55], v[32:47]
	ds_read_b64_tr_b16 v[52:53], v214 offset:0x600
	ds_read_b64_tr_b16 v[54:55], v214 offset:0xe00
	ds_read_b64_tr_b16 v[82:83], v214 offset:0x1600
	ds_read_b64_tr_b16 v[84:85], v214 offset:0x1e00
	ds_read_b64_tr_b16 v[88:89], v214 offset:0x2600
	ds_read_b64_tr_b16 v[90:91], v214 offset:0x2e00
	ds_read_b64_tr_b16 v[96:97], v214 offset:0x3600
	v_mfma_f32_32x32x16_bf16 v[32:47], v[64:67], v[56:59], v[32:47]
	ds_read_b64_tr_b16 v[98:99], v214 offset:0x3e00
	s_waitcnt lgkmcnt(0)
	v_mfma_f32_32x32x16_bf16 v[32:47], v[72:75], v[60:63], v[32:47]
	v_mfma_f32_32x32x16_bf16 v[48:63], v[48:51], v[52:55], 0
	s_waitcnt vmcnt(3) lgkmcnt(0)
	s_barrier
; template <int D0> __device__ __forceinline__ void pv_one(f32x16& od, int vb, bf16x8 pa0, bf16x8 pa1, bf16x8 pa2, bf16x8 pa3) {
;     ...
;     od = __builtin_amdgcn_mfma_f32_32x32x16_bf16(pa0, PK(l0, h0), od, 0, 0, 0);
;     od = __builtin_amdgcn_mfma_f32_32x32x16_bf16(pa1, PK(l1, h1), od, 0, 0, 0);
;     od = __builtin_amdgcn_mfma_f32_32x32x16_bf16(pa2, PK(l2, h2), od, 0, 0, 0);
;     od = __builtin_amdgcn_mfma_f32_32x32x16_bf16(pa3, PK(l3, h3), od, 0, 0, 0);
	v_lshl_add_u64 v[200:201], v[192:193], 0, s[46:47]
	v_lshl_add_u64 v[202:203], v[190:191], 0, s[50:51]
	v_lshl_add_u64 v[204:205], v[188:189], 0, s[50:51]
	v_lshl_add_u64 v[206:207], v[78:79], 0, s[62:63]
	v_lshl_add_u64 v[208:209], v[76:77], 0, s[62:63]
	v_mov_b32_e32 v81, v80
	v_mfma_f32_32x32x16_bf16 v[48:63], v[68:71], v[82:85], v[48:63]
	v_mov_b32_e32 v82, v80
	v_mov_b32_e32 v83, v80
	v_mov_b32_e32 v84, v80
	v_mov_b32_e32 v85, v80
	v_mov_b32_e32 v86, v80
	v_mov_b32_e32 v87, v80
	v_mov_b32_e32 v92, v80
	v_mfma_f32_32x32x16_bf16 v[48:63], v[64:67], v[88:91], v[48:63]
	v_mov_b32_e32 v88, v80
	v_mov_b32_e32 v89, v80
	v_mov_b32_e32 v90, v80
	v_mov_b32_e32 v91, v80
	v_mov_b32_e32 v93, v80
	v_mov_b32_e32 v94, v80
	v_mov_b32_e32 v95, v80
	v_mfma_f32_32x32x16_bf16 v[48:63], v[72:75], v[96:99], v[48:63]

;     __device__ __forceinline__ void operator()(const f32x4 (&acc)[2][2][4][2], const Unit& u, int wr, int wc, int fr, int fq) const {
;         const int t0 = row_off + u.pm * BM;
;         const int bi = t0 < 32768 ? (t0 >> 11) : 16 + ((t0 - 32768) >> 13);
;         const float* base = t0 < 32768 ? base_p : base_s;
;         const float* gp = mod + bi * 6144 + gate_off;
;         const int col0 = u.pn * BM + wc * 32 + 4 * fq;
;         f32x4 gv[2][2];
; #pragma unroll
;         for (int bj = 0; bj < 2; ++bj)
; #pragma unroll
;             for (int n = 0; n < 2; ++n) gv[bj][n] = *(const f32x4*)(gp + col0 + bj * HALF + n * 16);
; #pragma unroll
;         for (int ai = 0; ai < 2; ++ai)
; #pragma unroll
;             for (int m = 0; m < 4; ++m) { const size_t off = (size_t)(t0 + ai * HALF + wr * 64 + m * 16 + fr) * 1024 + col0;
; #pragma unroll
;                 for (int bj = 0; bj < 2; ++bj)
; #pragma unroll
;                     for (int n = 0; n < 2; ++n) { const f32x4 bs = *(const f32x4*)(base + off + bj * HALF + n * 16);
;                         *(f32x4*)(out + off + bj * HALF + n * 16) = bs + gv[bj][n] * acc[ai][bj][m][n]; } }
.LBB0_546:
	s_lshl_b32 s20, s44, 8
	s_add_i32 s13, s20, 0xffff8000
	s_lshr_b32 s13, s13, 13
	s_lshr_b32 s12, s44, 3
	s_add_i32 s13, s13, 16
	s_cmpk_lt_i32 s44, 0x80
	s_cselect_b32 s12, s12, s13
	s_mulk_i32 s12, 0x1800
	s_cselect_b32 s45, s17, s89
	s_cselect_b32 s44, s16, s88
	s_ashr_i32 s13, s12, 31
	v_add_u32_e32 v158, s20, v160
	s_lshl_b64 s[12:13], s[12:13], 2
	v_lshl_or_b32 v156, s77, 8, v162
	v_ashrrev_i32_e32 v159, 31, v158
	s_add_u32 s12, s34, s12
	v_ashrrev_i32_e32 v157, 31, v156
	v_lshlrev_b64 v[132:133], 10, v[158:159]
	s_addc_u32 s13, s35, s13
	v_lshl_add_u64 v[132:133], v[132:133], 0, v[156:157]
	v_lshl_add_u64 v[128:129], v[156:157], 2, s[12:13]
	v_lshlrev_b64 v[132:133], 2, v[132:133]
	v_add_co_u32_e32 v130, vcc, s69, v128
	v_lshl_add_u64 v[170:171], s[44:45], 0, v[132:133]
	s_nop 0
	v_addc_co_u32_e32 v131, vcc, 0, v129, vcc
	global_load_dwordx4 v[166:169], v[170:171], off
	global_load_dwordx4 v[140:143], v[130:131], off
	v_lshl_add_u64 v[172:173], s[54:55], 0, v[132:133]
	v_lshl_add_u64 v[128:129], v[128:129], 0, s[30:31]
	global_load_dwordx4 v[136:139], v[128:129], off offset:64
	global_load_dwordx4 v[132:135], v[128:129], off offset:512
	s_nop 0
	global_load_dwordx4 v[128:131], v[128:129], off offset:576
	s_andn2_b64 vcc, exec, s[6:7]
	s_mov_b64 s[6:7], -1
	s_waitcnt vmcnt(0)
	v_pk_fma_f32 v[126:127], v[126:127], v[142:143], v[168:169]
	v_pk_fma_f32 v[124:125], v[124:125], v[140:141], v[166:167]
	global_store_dwordx4 v[172:173], v[124:127], off
	global_load_dwordx4 v[124:127], v[170:171], off offset:64
	s_waitcnt vmcnt(0)
	v_pk_fma_f32 v[122:123], v[122:123], v[138:139], v[126:127]
	v_pk_fma_f32 v[120:121], v[120:121], v[136:137], v[124:125]
	global_store_dwordx4 v[172:173], v[120:123], off offset:64
	global_load_dwordx4 v[120:123], v[170:171], off offset:512
	s_waitcnt vmcnt(0)
	v_pk_fma_f32 v[118:119], v[118:119], v[134:135], v[122:123]
	v_pk_fma_f32 v[116:117], v[116:117], v[132:133], v[120:121]
	global_store_dwordx4 v[172:173], v[116:119], off offset:512
	global_load_dwordx4 v[116:119], v[170:171], off offset:576
	v_or_b32_e32 v120, 16, v158
	v_ashrrev_i32_e32 v121, 31, v120
	v_lshlrev_b64 v[120:121], 10, v[120:121]
	v_lshl_add_u64 v[120:121], v[120:121], 0, v[156:157]
	v_lshlrev_b64 v[120:121], 2, v[120:121]
	v_lshl_add_u64 v[122:123], s[44:45], 0, v[120:121]
	s_waitcnt vmcnt(0)
	v_pk_fma_f32 v[106:107], v[106:107], v[130:131], v[118:119]
	v_pk_fma_f32 v[104:105], v[104:105], v[128:129], v[116:117]
	global_store_dwordx4 v[172:173], v[104:107], off offset:576
	global_load_dwordx4 v[104:107], v[122:123], off
	v_lshl_add_u64 v[116:117], s[54:55], 0, v[120:121]
	s_waitcnt vmcnt(0)
	v_pk_fma_f32 v[106:107], v[114:115], v[142:143], v[106:107]
	v_pk_fma_f32 v[104:105], v[112:113], v[140:141], v[104:105]
	global_store_dwordx4 v[116:117], v[104:107], off
	global_load_dwordx4 v[104:107], v[122:123], off offset:64
	s_waitcnt vmcnt(0)
	v_pk_fma_f32 v[106:107], v[110:111], v[138:139], v[106:107]
	v_pk_fma_f32 v[104:105], v[108:109], v[136:137], v[104:105]
	global_store_dwordx4 v[116:117], v[104:107], off offset:64
	global_load_dwordx4 v[104:107], v[122:123], off offset:512
	s_waitcnt vmcnt(0)
	v_pk_fma_f32 v[102:103], v[102:103], v[134:135], v[106:107]
	v_pk_fma_f32 v[100:101], v[100:101], v[132:133], v[104:105]
	global_store_dwordx4 v[116:117], v[100:103], off offset:512
	global_load_dwordx4 v[100:103], v[122:123], off offset:576
	v_or_b32_e32 v104, 32, v158
	v_ashrrev_i32_e32 v105, 31, v104
	v_lshlrev_b64 v[104:105], 10, v[104:105]
	v_lshl_add_u64 v[104:105], v[104:105], 0, v[156:157]
	v_lshlrev_b64 v[104:105], 2, v[104:105]
	v_lshl_add_u64 v[106:107], s[44:45], 0, v[104:105]
	s_waitcnt vmcnt(0)
	v_pk_fma_f32 v[90:91], v[90:91], v[130:131], v[102:103]
	v_pk_fma_f32 v[88:89], v[88:89], v[128:129], v[100:101]
	global_store_dwordx4 v[116:117], v[88:91], off offset:576
	global_load_dwordx4 v[88:91], v[106:107], off
	v_lshl_add_u64 v[100:101], s[54:55], 0, v[104:105]
	s_waitcnt vmcnt(0)
	v_pk_fma_f32 v[90:91], v[98:99], v[142:143], v[90:91]
	v_pk_fma_f32 v[88:89], v[96:97], v[140:141], v[88:89]
	global_store_dwordx4 v[100:101], v[88:91], off
	global_load_dwordx4 v[88:91], v[106:107], off offset:64
	s_waitcnt vmcnt(0)
	v_pk_fma_f32 v[90:91], v[94:95], v[138:139], v[90:91]
	v_pk_fma_f32 v[88:89], v[92:93], v[136:137], v[88:89]
	global_store_dwordx4 v[100:101], v[88:91], off offset:64
	global_load_dwordx4 v[88:91], v[106:107], off offset:512
	s_waitcnt vmcnt(0)
	v_pk_fma_f32 v[86:87], v[86:87], v[134:135], v[90:91]
	v_pk_fma_f32 v[84:85], v[84:85], v[132:133], v[88:89]
	global_store_dwordx4 v[100:101], v[84:87], off offset:512
	global_load_dwordx4 v[84:87], v[106:107], off offset:576
	v_or_b32_e32 v88, 48, v158
	v_ashrrev_i32_e32 v89, 31, v88
	v_lshlrev_b64 v[88:89], 10, v[88:89]
	v_lshl_add_u64 v[88:89], v[88:89], 0, v[156:157]
	v_lshlrev_b64 v[88:89], 2, v[88:89]
	v_lshl_add_u64 v[90:91], s[44:45], 0, v[88:89]
	s_waitcnt vmcnt(0)
	v_pk_fma_f32 v[74:75], v[74:75], v[130:131], v[86:87]
	v_pk_fma_f32 v[72:73], v[72:73], v[128:129], v[84:85]
	global_store_dwordx4 v[100:101], v[72:75], off offset:576
	global_load_dwordx4 v[72:75], v[90:91], off
	v_lshl_add_u64 v[84:85], s[54:55], 0, v[88:89]
	s_waitcnt vmcnt(0)
	v_pk_fma_f32 v[74:75], v[82:83], v[142:143], v[74:75]
	v_pk_fma_f32 v[72:73], v[80:81], v[140:141], v[72:73]
	global_store_dwordx4 v[84:85], v[72:75], off
	global_load_dwordx4 v[72:75], v[90:91], off offset:64
	s_waitcnt vmcnt(0)
;     __device__ __forceinline__ void operator()(const f32x4 (&acc)[2][2][4][2], const Unit& u, int wr, int wc, int fr, int fq) const {
;     ...
;             for (int m = 0; m < 4; ++m) { const size_t off = (size_t)(t0 + ai * HALF + wr * 64 + m * 16 + fr) * 1024 + col0;
; #pragma unroll
;                 for (int bj = 0; bj < 2; ++bj)
; #pragma unroll
;                     for (int n = 0; n < 2; ++n) { const f32x4 bs = *(const f32x4*)(base + off + bj * HALF + n * 16);
;                         *(f32x4*)(out + off + bj * HALF + n * 16) = bs + gv[bj][n] * acc[ai][bj][m][n]; } }
	v_pk_fma_f32 v[74:75], v[78:79], v[138:139], v[74:75]
	v_pk_fma_f32 v[72:73], v[76:77], v[136:137], v[72:73]
	global_store_dwordx4 v[84:85], v[72:75], off offset:64
	global_load_dwordx4 v[72:75], v[90:91], off offset:512
	s_waitcnt vmcnt(0)
	v_pk_fma_f32 v[70:71], v[70:71], v[134:135], v[74:75]
	v_pk_fma_f32 v[68:69], v[68:69], v[132:133], v[72:73]
	global_store_dwordx4 v[84:85], v[68:71], off offset:512
	global_load_dwordx4 v[68:71], v[90:91], off offset:576
	v_add_u32_e32 v72, 0x80, v158
	v_ashrrev_i32_e32 v73, 31, v72
	v_lshlrev_b64 v[72:73], 10, v[72:73]
	v_lshl_add_u64 v[72:73], v[72:73], 0, v[156:157]
	v_lshlrev_b64 v[72:73], 2, v[72:73]
	v_lshl_add_u64 v[74:75], s[44:45], 0, v[72:73]
	s_waitcnt vmcnt(0)
	v_pk_fma_f32 v[66:67], v[66:67], v[130:131], v[70:71]
	v_pk_fma_f32 v[64:65], v[64:65], v[128:129], v[68:69]
	global_store_dwordx4 v[84:85], v[64:67], off offset:576
	global_load_dwordx4 v[64:67], v[74:75], off
	v_lshl_add_u64 v[68:69], s[54:55], 0, v[72:73]
	s_waitcnt vmcnt(0)
	v_pk_fma_f32 v[62:63], v[62:63], v[142:143], v[66:67]
	v_pk_fma_f32 v[60:61], v[60:61], v[140:141], v[64:65]
	global_store_dwordx4 v[68:69], v[60:63], off
	global_load_dwordx4 v[60:63], v[74:75], off offset:64
	s_waitcnt vmcnt(0)
	v_pk_fma_f32 v[58:59], v[58:59], v[138:139], v[62:63]
	v_pk_fma_f32 v[56:57], v[56:57], v[136:137], v[60:61]
	global_store_dwordx4 v[68:69], v[56:59], off offset:64
	global_load_dwordx4 v[56:59], v[74:75], off offset:512
	s_waitcnt vmcnt(0)
	v_pk_fma_f32 v[54:55], v[54:55], v[134:135], v[58:59]
	v_pk_fma_f32 v[52:53], v[52:53], v[132:133], v[56:57]
	global_store_dwordx4 v[68:69], v[52:55], off offset:512
	global_load_dwordx4 v[52:55], v[74:75], off offset:576
	v_add_u32_e32 v56, 0x90, v158
	v_ashrrev_i32_e32 v57, 31, v56
	v_lshlrev_b64 v[56:57], 10, v[56:57]
	v_lshl_add_u64 v[56:57], v[56:57], 0, v[156:157]
	v_lshlrev_b64 v[56:57], 2, v[56:57]
	v_lshl_add_u64 v[58:59], s[44:45], 0, v[56:57]
	s_waitcnt vmcnt(0)
	v_pk_fma_f32 v[42:43], v[42:43], v[130:131], v[54:55]
	v_pk_fma_f32 v[40:41], v[40:41], v[128:129], v[52:53]
	global_store_dwordx4 v[68:69], v[40:43], off offset:576
	global_load_dwordx4 v[40:43], v[58:59], off
	v_lshl_add_u64 v[52:53], s[54:55], 0, v[56:57]
	s_waitcnt vmcnt(0)
	v_pk_fma_f32 v[42:43], v[50:51], v[142:143], v[42:43]
	v_pk_fma_f32 v[40:41], v[48:49], v[140:141], v[40:41]
	global_store_dwordx4 v[52:53], v[40:43], off
	global_load_dwordx4 v[40:43], v[58:59], off offset:64
	s_waitcnt vmcnt(0)
	v_pk_fma_f32 v[42:43], v[46:47], v[138:139], v[42:43]
	v_pk_fma_f32 v[40:41], v[44:45], v[136:137], v[40:41]
	global_store_dwordx4 v[52:53], v[40:43], off offset:64
	global_load_dwordx4 v[40:43], v[58:59], off offset:512
	s_waitcnt vmcnt(0)
	v_pk_fma_f32 v[38:39], v[38:39], v[134:135], v[42:43]
	v_pk_fma_f32 v[36:37], v[36:37], v[132:133], v[40:41]
	global_store_dwordx4 v[52:53], v[36:39], off offset:512
	global_load_dwordx4 v[36:39], v[58:59], off offset:576
	v_add_u32_e32 v40, 0xa0, v158
	v_ashrrev_i32_e32 v41, 31, v40
	v_lshlrev_b64 v[40:41], 10, v[40:41]
	v_lshl_add_u64 v[40:41], v[40:41], 0, v[156:157]
	v_lshlrev_b64 v[40:41], 2, v[40:41]
	v_lshl_add_u64 v[42:43], s[44:45], 0, v[40:41]
	s_waitcnt vmcnt(0)
	v_pk_fma_f32 v[26:27], v[26:27], v[130:131], v[38:39]
	v_pk_fma_f32 v[24:25], v[24:25], v[128:129], v[36:37]
	global_store_dwordx4 v[52:53], v[24:27], off offset:576
	global_load_dwordx4 v[24:27], v[42:43], off
	v_lshl_add_u64 v[36:37], s[54:55], 0, v[40:41]
	s_waitcnt vmcnt(0)
	v_pk_fma_f32 v[26:27], v[34:35], v[142:143], v[26:27]
	v_pk_fma_f32 v[24:25], v[32:33], v[140:141], v[24:25]
	global_store_dwordx4 v[36:37], v[24:27], off
	global_load_dwordx4 v[24:27], v[42:43], off offset:64
	s_waitcnt vmcnt(0)
	v_pk_fma_f32 v[26:27], v[30:31], v[138:139], v[26:27]
	v_pk_fma_f32 v[24:25], v[28:29], v[136:137], v[24:25]
	global_store_dwordx4 v[36:37], v[24:27], off offset:64
	global_load_dwordx4 v[24:27], v[42:43], off offset:512
	s_waitcnt vmcnt(0)
	v_pk_fma_f32 v[22:23], v[22:23], v[134:135], v[26:27]
	v_pk_fma_f32 v[20:21], v[20:21], v[132:133], v[24:25]
	global_store_dwordx4 v[36:37], v[20:23], off offset:512
	global_load_dwordx4 v[20:23], v[42:43], off offset:576
	v_add_u32_e32 v24, 0xb0, v158
	v_ashrrev_i32_e32 v25, 31, v24
	v_lshlrev_b64 v[24:25], 10, v[24:25]
	v_lshl_add_u64 v[24:25], v[24:25], 0, v[156:157]
	v_lshlrev_b64 v[24:25], 2, v[24:25]
	v_lshl_add_u64 v[26:27], s[44:45], 0, v[24:25]
	s_waitcnt vmcnt(0)
	v_pk_fma_f32 v[10:11], v[10:11], v[130:131], v[22:23]
	v_pk_fma_f32 v[8:9], v[8:9], v[128:129], v[20:21]
	global_store_dwordx4 v[36:37], v[8:11], off offset:576
	global_load_dwordx4 v[8:11], v[26:27], off
	v_lshl_add_u64 v[20:21], s[54:55], 0, v[24:25]
	s_waitcnt vmcnt(0)
	v_pk_fma_f32 v[10:11], v[18:19], v[142:143], v[10:11]
	v_pk_fma_f32 v[8:9], v[16:17], v[140:141], v[8:9]
	global_store_dwordx4 v[20:21], v[8:11], off
	global_load_dwordx4 v[8:11], v[26:27], off offset:64
	s_waitcnt vmcnt(0)
	v_pk_fma_f32 v[10:11], v[14:15], v[138:139], v[10:11]
	v_pk_fma_f32 v[8:9], v[12:13], v[136:137], v[8:9]
	global_store_dwordx4 v[20:21], v[8:11], off offset:64
	global_load_dwordx4 v[8:11], v[26:27], off offset:512
	s_waitcnt vmcnt(0)
	v_pk_fma_f32 v[6:7], v[6:7], v[134:135], v[10:11]
	v_pk_fma_f32 v[4:5], v[4:5], v[132:133], v[8:9]
	global_store_dwordx4 v[20:21], v[4:7], off offset:512
	global_load_dwordx4 v[4:7], v[26:27], off offset:576
	s_waitcnt vmcnt(0)
	v_pk_fma_f32 v[2:3], v[2:3], v[130:131], v[6:7]
	v_pk_fma_f32 v[0:1], v[0:1], v[128:129], v[4:5]
	global_store_dwordx4 v[20:21], v[0:3], off offset:576
	s_cbranch_vccnz .LBB0_539
	s_andn2_b64 vcc, exec, s[0:1]
	s_cbranch_vccnz .LBB0_538
	s_barrier
	s_branch .LBB0_538

;     __device__ __forceinline__ void operator()(const f32x4 (&acc)[2][2][4][2], const Unit& u, int wr, int wc, int fr, int fq) const {
;         const int t0 = row_off + u.pm * BM;
;         const int bi = t0 < 32768 ? (t0 >> 11) : 16 + ((t0 - 32768) >> 13);
;         const float* base = t0 < 32768 ? base_p : base_s;
;         const float* gp = mod + bi * 6144 + gate_off;
;         const int col0 = u.pn * BM + wc * 32 + 4 * fq;
;         f32x4 gv[2][2];
; #pragma unroll
;         for (int bj = 0; bj < 2; ++bj)
; #pragma unroll
;             for (int n = 0; n < 2; ++n) gv[bj][n] = *(const f32x4*)(gp + col0 + bj * HALF + n * 16);
; #pragma unroll
;         for (int ai = 0; ai < 2; ++ai)
; #pragma unroll
;             for (int m = 0; m < 4; ++m) { const size_t off = (size_t)(t0 + ai * HALF + wr * 64 + m * 16 + fr) * 1024 + col0;
; #pragma unroll
;                 for (int bj = 0; bj < 2; ++bj)
; #pragma unroll
;                     for (int n = 0; n < 2; ++n) { const f32x4 bs = *(const f32x4*)(base + off + bj * HALF + n * 16);
;                         *(f32x4*)(out + off + bj * HALF + n * 16) = bs + gv[bj][n] * acc[ai][bj][m][n]; } }
.LBB0_825:
	s_lshl_b32 s20, s66, 8
	s_add_i32 s13, s20, 0xffff8000
	s_lshr_b32 s13, s13, 13
	s_lshr_b32 s12, s66, 3
	s_add_i32 s13, s13, 16
	s_cmpk_lt_i32 s66, 0x80
	s_cselect_b32 s12, s12, s13
	s_mulk_i32 s12, 0x1800
	s_ashr_i32 s13, s12, 31
	s_lshl_b64 s[12:13], s[12:13], 2
	v_lshl_or_b32 v64, s68, 8, v160
	s_add_u32 s12, s34, s12
	v_ashrrev_i32_e32 v65, 31, v64
	v_add_u32_e32 v156, s20, v158
	s_addc_u32 s13, s35, s13
	v_lshlrev_b64 v[154:155], 2, v[64:65]
	v_ashrrev_i32_e32 v157, 31, v156
	v_lshl_add_u64 v[64:65], s[12:13], 0, v[154:155]
	v_lshlrev_b64 v[164:165], 12, v[156:157]
	v_lshl_add_u64 v[66:67], v[64:65], 0, s[16:17]
	v_add_co_u32_e32 v64, vcc, s62, v64
	v_lshl_add_u64 v[164:165], s[54:55], 0, v[164:165]
	s_nop 0
	v_addc_co_u32_e32 v65, vcc, 0, v65, vcc
	v_lshl_add_u64 v[168:169], v[164:165], 0, v[154:155]
	global_load_dwordx4 v[120:123], v[64:65], off
	global_load_dwordx4 v[112:115], v[66:67], off offset:64
	global_load_dwordx4 v[108:111], v[66:67], off offset:512
	s_nop 0
	global_load_dwordx4 v[64:67], v[66:67], off offset:576
	s_mov_b64 s[28:29], -1
	global_load_dwordx4 v[164:167], v[168:169], off
	s_and_b64 vcc, exec, s[4:5]
	s_waitcnt vmcnt(0)
	v_pk_fma_f32 v[142:143], v[142:143], v[122:123], v[166:167]
	v_pk_fma_f32 v[140:141], v[140:141], v[120:121], v[164:165]
	global_store_dwordx4 v[168:169], v[140:143], off
	global_load_dwordx4 v[140:143], v[168:169], off offset:64
	s_waitcnt vmcnt(0)
	v_pk_fma_f32 v[138:139], v[138:139], v[114:115], v[142:143]
	v_pk_fma_f32 v[136:137], v[136:137], v[112:113], v[140:141]
	global_store_dwordx4 v[168:169], v[136:139], off offset:64
	global_load_dwordx4 v[136:139], v[168:169], off offset:512
	s_waitcnt vmcnt(0)
	v_pk_fma_f32 v[134:135], v[134:135], v[110:111], v[138:139]
	v_pk_fma_f32 v[132:133], v[132:133], v[108:109], v[136:137]
	global_store_dwordx4 v[168:169], v[132:135], off offset:512
	global_load_dwordx4 v[132:135], v[168:169], off offset:576
	s_waitcnt vmcnt(0)
	v_pk_fma_f32 v[130:131], v[130:131], v[66:67], v[134:135]
	v_pk_fma_f32 v[128:129], v[128:129], v[64:65], v[132:133]
	global_store_dwordx4 v[168:169], v[128:131], off offset:576
	s_nop 1
	v_or_b32_e32 v128, 16, v156
	v_ashrrev_i32_e32 v129, 31, v128
	v_lshlrev_b64 v[128:129], 12, v[128:129]
	v_lshl_add_u64 v[128:129], s[54:55], 0, v[128:129]
	v_lshl_add_u64 v[132:133], v[128:129], 0, v[154:155]
	global_load_dwordx4 v[128:131], v[132:133], off
	s_waitcnt vmcnt(0)
	v_pk_fma_f32 v[126:127], v[126:127], v[122:123], v[130:131]
	v_pk_fma_f32 v[124:125], v[124:125], v[120:121], v[128:129]
	global_store_dwordx4 v[132:133], v[124:127], off
	global_load_dwordx4 v[124:127], v[132:133], off offset:64
	s_waitcnt vmcnt(0)
	v_pk_fma_f32 v[118:119], v[118:119], v[114:115], v[126:127]
	v_pk_fma_f32 v[116:117], v[116:117], v[112:113], v[124:125]
	global_store_dwordx4 v[132:133], v[116:119], off offset:64
	global_load_dwordx4 v[116:119], v[132:133], off offset:512
	s_waitcnt vmcnt(0)
	v_pk_fma_f32 v[106:107], v[106:107], v[110:111], v[118:119]
	v_pk_fma_f32 v[104:105], v[104:105], v[108:109], v[116:117]
	global_store_dwordx4 v[132:133], v[104:107], off offset:512
	global_load_dwordx4 v[104:107], v[132:133], off offset:576
	s_waitcnt vmcnt(0)
	v_pk_fma_f32 v[102:103], v[102:103], v[66:67], v[106:107]
	v_pk_fma_f32 v[100:101], v[100:101], v[64:65], v[104:105]
	global_store_dwordx4 v[132:133], v[100:103], off offset:576
	s_nop 1
	v_or_b32_e32 v100, 32, v156
	v_ashrrev_i32_e32 v101, 31, v100
	v_lshlrev_b64 v[100:101], 12, v[100:101]
	v_lshl_add_u64 v[100:101], s[54:55], 0, v[100:101]
	v_lshl_add_u64 v[104:105], v[100:101], 0, v[154:155]
	global_load_dwordx4 v[100:103], v[104:105], off
	s_waitcnt vmcnt(0)
	v_pk_fma_f32 v[98:99], v[98:99], v[122:123], v[102:103]
	v_pk_fma_f32 v[96:97], v[96:97], v[120:121], v[100:101]
	global_store_dwordx4 v[104:105], v[96:99], off
	global_load_dwordx4 v[96:99], v[104:105], off offset:64
	s_waitcnt vmcnt(0)
	v_pk_fma_f32 v[94:95], v[94:95], v[114:115], v[98:99]
	v_pk_fma_f32 v[92:93], v[92:93], v[112:113], v[96:97]
	global_store_dwordx4 v[104:105], v[92:95], off offset:64
	global_load_dwordx4 v[92:95], v[104:105], off offset:512
	s_waitcnt vmcnt(0)
	v_pk_fma_f32 v[90:91], v[90:91], v[110:111], v[94:95]
	v_pk_fma_f32 v[88:89], v[88:89], v[108:109], v[92:93]
	global_store_dwordx4 v[104:105], v[88:91], off offset:512
	global_load_dwordx4 v[88:91], v[104:105], off offset:576
	s_waitcnt vmcnt(0)
	v_pk_fma_f32 v[86:87], v[86:87], v[66:67], v[90:91]
	v_pk_fma_f32 v[84:85], v[84:85], v[64:65], v[88:89]
	global_store_dwordx4 v[104:105], v[84:87], off offset:576
	s_nop 1
	v_or_b32_e32 v84, 48, v156
	v_ashrrev_i32_e32 v85, 31, v84
	v_lshlrev_b64 v[84:85], 12, v[84:85]
	v_lshl_add_u64 v[84:85], s[54:55], 0, v[84:85]
	v_lshl_add_u64 v[88:89], v[84:85], 0, v[154:155]
	global_load_dwordx4 v[84:87], v[88:89], off
	s_waitcnt vmcnt(0)
	v_pk_fma_f32 v[82:83], v[82:83], v[122:123], v[86:87]
	v_pk_fma_f32 v[80:81], v[80:81], v[120:121], v[84:85]
	global_store_dwordx4 v[88:89], v[80:83], off
	global_load_dwordx4 v[80:83], v[88:89], off offset:64
	s_waitcnt vmcnt(0)
	v_pk_fma_f32 v[78:79], v[78:79], v[114:115], v[82:83]
	v_pk_fma_f32 v[76:77], v[76:77], v[112:113], v[80:81]
	global_store_dwordx4 v[88:89], v[76:79], off offset:64
	global_load_dwordx4 v[76:79], v[88:89], off offset:512
	s_waitcnt vmcnt(0)
;     __device__ __forceinline__ void operator()(const f32x4 (&acc)[2][2][4][2], const Unit& u, int wr, int wc, int fr, int fq) const {
;     ...
;             for (int m = 0; m < 4; ++m) { const size_t off = (size_t)(t0 + ai * HALF + wr * 64 + m * 16 + fr) * 1024 + col0;
; #pragma unroll
;                 for (int bj = 0; bj < 2; ++bj)
; #pragma unroll
;                     for (int n = 0; n < 2; ++n) { const f32x4 bs = *(const f32x4*)(base + off + bj * HALF + n * 16);
;                         *(f32x4*)(out + off + bj * HALF + n * 16) = bs + gv[bj][n] * acc[ai][bj][m][n]; } }
	v_pk_fma_f32 v[74:75], v[74:75], v[110:111], v[78:79]
	v_pk_fma_f32 v[72:73], v[72:73], v[108:109], v[76:77]
	global_store_dwordx4 v[88:89], v[72:75], off offset:512
	global_load_dwordx4 v[72:75], v[88:89], off offset:576
	s_waitcnt vmcnt(0)
	v_pk_fma_f32 v[70:71], v[70:71], v[66:67], v[74:75]
	v_pk_fma_f32 v[68:69], v[68:69], v[64:65], v[72:73]
	global_store_dwordx4 v[88:89], v[68:71], off offset:576
	s_nop 1
	v_add_u32_e32 v68, 0x80, v156
	v_ashrrev_i32_e32 v69, 31, v68
	v_lshlrev_b64 v[68:69], 12, v[68:69]
	v_lshl_add_u64 v[68:69], s[54:55], 0, v[68:69]
	v_lshl_add_u64 v[72:73], v[68:69], 0, v[154:155]
	global_load_dwordx4 v[68:71], v[72:73], off
	s_waitcnt vmcnt(0)
	v_pk_fma_f32 v[62:63], v[62:63], v[122:123], v[70:71]
	v_pk_fma_f32 v[60:61], v[60:61], v[120:121], v[68:69]
	global_store_dwordx4 v[72:73], v[60:63], off
	global_load_dwordx4 v[60:63], v[72:73], off offset:64
	s_waitcnt vmcnt(0)
	v_pk_fma_f32 v[58:59], v[58:59], v[114:115], v[62:63]
	v_pk_fma_f32 v[56:57], v[56:57], v[112:113], v[60:61]
	global_store_dwordx4 v[72:73], v[56:59], off offset:64
	global_load_dwordx4 v[56:59], v[72:73], off offset:512
	s_waitcnt vmcnt(0)
	v_pk_fma_f32 v[54:55], v[54:55], v[110:111], v[58:59]
	v_pk_fma_f32 v[52:53], v[52:53], v[108:109], v[56:57]
	global_store_dwordx4 v[72:73], v[52:55], off offset:512
	global_load_dwordx4 v[52:55], v[72:73], off offset:576
	s_waitcnt vmcnt(0)
	v_pk_fma_f32 v[50:51], v[50:51], v[66:67], v[54:55]
	v_pk_fma_f32 v[48:49], v[48:49], v[64:65], v[52:53]
	global_store_dwordx4 v[72:73], v[48:51], off offset:576
	s_nop 1
	v_add_u32_e32 v48, 0x90, v156
	v_ashrrev_i32_e32 v49, 31, v48
	v_lshlrev_b64 v[48:49], 12, v[48:49]
	v_lshl_add_u64 v[48:49], s[54:55], 0, v[48:49]
	v_lshl_add_u64 v[52:53], v[48:49], 0, v[154:155]
	global_load_dwordx4 v[48:51], v[52:53], off
	s_waitcnt vmcnt(0)
	v_pk_fma_f32 v[46:47], v[46:47], v[122:123], v[50:51]
	v_pk_fma_f32 v[44:45], v[44:45], v[120:121], v[48:49]
	global_store_dwordx4 v[52:53], v[44:47], off
	global_load_dwordx4 v[44:47], v[52:53], off offset:64
	s_waitcnt vmcnt(0)
	v_pk_fma_f32 v[42:43], v[42:43], v[114:115], v[46:47]
	v_pk_fma_f32 v[40:41], v[40:41], v[112:113], v[44:45]
	global_store_dwordx4 v[52:53], v[40:43], off offset:64
	global_load_dwordx4 v[40:43], v[52:53], off offset:512
	s_waitcnt vmcnt(0)
	v_pk_fma_f32 v[38:39], v[38:39], v[110:111], v[42:43]
	v_pk_fma_f32 v[36:37], v[36:37], v[108:109], v[40:41]
	global_store_dwordx4 v[52:53], v[36:39], off offset:512
	global_load_dwordx4 v[36:39], v[52:53], off offset:576
	s_waitcnt vmcnt(0)
	v_pk_fma_f32 v[34:35], v[34:35], v[66:67], v[38:39]
	v_pk_fma_f32 v[32:33], v[32:33], v[64:65], v[36:37]
	global_store_dwordx4 v[52:53], v[32:35], off offset:576
	s_nop 1
	v_add_u32_e32 v32, 0xa0, v156
	v_ashrrev_i32_e32 v33, 31, v32
	v_lshlrev_b64 v[32:33], 12, v[32:33]
	v_lshl_add_u64 v[32:33], s[54:55], 0, v[32:33]
	v_lshl_add_u64 v[36:37], v[32:33], 0, v[154:155]
	global_load_dwordx4 v[32:35], v[36:37], off
	s_waitcnt vmcnt(0)
	v_pk_fma_f32 v[30:31], v[30:31], v[122:123], v[34:35]
	v_pk_fma_f32 v[28:29], v[28:29], v[120:121], v[32:33]
	global_store_dwordx4 v[36:37], v[28:31], off
	global_load_dwordx4 v[28:31], v[36:37], off offset:64
	s_waitcnt vmcnt(0)
	v_pk_fma_f32 v[26:27], v[26:27], v[114:115], v[30:31]
	v_pk_fma_f32 v[24:25], v[24:25], v[112:113], v[28:29]
	global_store_dwordx4 v[36:37], v[24:27], off offset:64
	global_load_dwordx4 v[24:27], v[36:37], off offset:512
	s_waitcnt vmcnt(0)
	v_pk_fma_f32 v[22:23], v[22:23], v[110:111], v[26:27]
	v_pk_fma_f32 v[20:21], v[20:21], v[108:109], v[24:25]
	global_store_dwordx4 v[36:37], v[20:23], off offset:512
	global_load_dwordx4 v[20:23], v[36:37], off offset:576
	s_waitcnt vmcnt(0)
	v_pk_fma_f32 v[14:15], v[14:15], v[66:67], v[22:23]
	v_pk_fma_f32 v[12:13], v[12:13], v[64:65], v[20:21]
	global_store_dwordx4 v[36:37], v[12:15], off offset:576
	s_nop 1
	v_add_u32_e32 v12, 0xb0, v156
	v_ashrrev_i32_e32 v13, 31, v12
	v_lshlrev_b64 v[12:13], 12, v[12:13]
	v_lshl_add_u64 v[12:13], s[54:55], 0, v[12:13]
	v_lshl_add_u64 v[12:13], v[12:13], 0, v[154:155]
	global_load_dwordx4 v[20:23], v[12:13], off
	s_waitcnt vmcnt(0)
	v_pk_fma_f32 v[18:19], v[18:19], v[122:123], v[22:23]
	v_pk_fma_f32 v[16:17], v[16:17], v[120:121], v[20:21]
	global_store_dwordx4 v[12:13], v[16:19], off
	global_load_dwordx4 v[14:17], v[12:13], off offset:64
	s_waitcnt vmcnt(0)
	v_pk_fma_f32 v[10:11], v[10:11], v[114:115], v[16:17]
	v_pk_fma_f32 v[8:9], v[8:9], v[112:113], v[14:15]
	global_store_dwordx4 v[12:13], v[8:11], off offset:64
	global_load_dwordx4 v[8:11], v[12:13], off offset:512
	s_waitcnt vmcnt(0)
	v_pk_fma_f32 v[6:7], v[6:7], v[110:111], v[10:11]
	v_pk_fma_f32 v[4:5], v[4:5], v[108:109], v[8:9]
	global_store_dwordx4 v[12:13], v[4:7], off offset:512
	global_load_dwordx4 v[4:7], v[12:13], off offset:576
	s_waitcnt vmcnt(0)
	v_pk_fma_f32 v[2:3], v[2:3], v[66:67], v[6:7]
	v_pk_fma_f32 v[0:1], v[0:1], v[64:65], v[4:5]
	global_store_dwordx4 v[12:13], v[0:3], off offset:576
	s_cbranch_vccnz .LBB0_809
	s_andn2_b64 vcc, exec, s[0:1]
	s_cbranch_vccnz .LBB0_808
	s_barrier
	s_branch .LBB0_808

; __global__ void __launch_bounds__(512, 2) fwd_kernel(Args args) {
	.amdhsa_kernel _Z10fwd_kernel4Args
		.amdhsa_group_segment_fixed_size 0
		.amdhsa_private_segment_fixed_size 0
		.amdhsa_kernarg_size 440
		.amdhsa_user_sgpr_count 2
		.amdhsa_user_sgpr_dispatch_ptr 0
		.amdhsa_user_sgpr_queue_ptr 0
		.amdhsa_user_sgpr_kernarg_segment_ptr 1
		.amdhsa_user_sgpr_dispatch_id 0
		.amdhsa_user_sgpr_kernarg_preload_length 0
		.amdhsa_user_sgpr_kernarg_preload_offset 0
		.amdhsa_user_sgpr_private_segment_size 0
		.amdhsa_uses_dynamic_stack 0
		.amdhsa_enable_private_segment 0
		.amdhsa_system_sgpr_workgroup_id_x 1
		.amdhsa_system_sgpr_workgroup_id_y 0
		.amdhsa_system_sgpr_workgroup_id_z 0
		.amdhsa_system_sgpr_workgroup_info 0
		.amdhsa_system_vgpr_workitem_id 2
		.amdhsa_next_free_vgpr 245
		.amdhsa_next_free_sgpr 98
		.amdhsa_accum_offset 248
		.amdhsa_reserve_vcc 1
		.amdhsa_float_round_mode_32 0
		.amdhsa_float_round_mode_16_64 0
		.amdhsa_float_denorm_mode_32 3
		.amdhsa_float_denorm_mode_16_64 3
		.amdhsa_dx10_clamp 1
		.amdhsa_ieee_mode 1
		.amdhsa_fp16_overflow 0
		.amdhsa_tg_split 0
		.amdhsa_exception_fp_ieee_invalid_op 0
		.amdhsa_exception_fp_denorm_src 0
		.amdhsa_exception_fp_ieee_div_zero 0
		.amdhsa_exception_fp_ieee_overflow 0
		.amdhsa_exception_fp_ieee_underflow 0
		.amdhsa_exception_fp_ieee_inexact 0
		.amdhsa_exception_int_div_zero 0
	.end_amdhsa_kernel

; __global__ void __launch_bounds__(512, 2) fwd_kernel(Args args) {
amdhsa.kernels:
  - .agpr_count:     0
    .args:
      - .offset:         0
        .size:           184
        .value_kind:     by_value
      - .offset:         184
        .size:           4
        .value_kind:     hidden_block_count_x
      - .offset:         188
        .size:           4
        .value_kind:     hidden_block_count_y
      - .offset:         192
        .size:           4
        .value_kind:     hidden_block_count_z
      - .offset:         196
        .size:           2
        .value_kind:     hidden_group_size_x
      - .offset:         198
        .size:           2
        .value_kind:     hidden_group_size_y
      - .offset:         200
        .size:           2
        .value_kind:     hidden_group_size_z
      - .offset:         202
        .size:           2
        .value_kind:     hidden_remainder_x
      - .offset:         204
        .size:           2
        .value_kind:     hidden_remainder_y
      - .offset:         206
        .size:           2
        .value_kind:     hidden_remainder_z
      - .offset:         224
        .size:           8
        .value_kind:     hidden_global_offset_x
      - .offset:         232
        .size:           8
        .value_kind:     hidden_global_offset_y
      - .offset:         240
        .size:           8
        .value_kind:     hidden_global_offset_z
      - .offset:         248
        .size:           2
        .value_kind:     hidden_grid_dims
      - .offset:         272
        .size:           8
        .value_kind:     hidden_multigrid_sync_arg
      - .offset:         304
        .size:           4
        .value_kind:     hidden_dynamic_lds_size
    .group_segment_fixed_size: 0
    .kernarg_segment_align: 8
    .kernarg_segment_size: 440
    .language:       OpenCL C
    .language_version:
      - 2
      - 0
    .max_flat_workgroup_size: 512
    .name:           _Z10fwd_kernel4Args
    .private_segment_fixed_size: 0
    .sgpr_count:     104
    .sgpr_spill_count: 35
    .symbol:         _Z10fwd_kernel4Args.kd
    .uniform_work_group_size: 1
    .uses_dynamic_stack: false
    .vgpr_count:     245
    .vgpr_spill_count: 0
    .wavefront_size: 64
